# swapred: 95 ds_bpermute butterfly steps (xor16/xor32) in EpiRes x4 and EpiSoftmax replaced by v_permlane16/32_swap (no LDS round trip)
# baseline (speedup 1.0000x reference)
; __device__ __forceinline__ float bflo(unsigned w) { return __uint_as_float(w << 16); }
; __device__ __forceinline__ float bfhi(unsigned w) { return __uint_as_float(w & 0xffff0000u); }
; __device__ __forceinline__ v4u pack8(const f32x4 a, const f32x4 b) { v4u w; w.x = cvt_pk_bf16(a[0], a[1]); w.y = cvt_pk_bf16(a[2], a[3]); w.z = cvt_pk_bf16(b[0], b[1]); w.w = cvt_pk_bf16(b[2], b[3]); return w; }
;     __device__ __forceinline__ void operator()(const f32x4 (&acc)[2][2][4][2], const pg8::Unit& u, int wr, int wc, int fr, int fq) const {
;         const int row0 = u.pm * 256 + wr * 64 + fr, col0 = u.pn * 256 + wc * 32 + 8 * fq;
; #pragma unroll
;         for (int ai = 0; ai < 2; ++ai)
; #pragma unroll
;             for (int m = 0; m < 4; ++m) {
;                 const int row = row0 + ai * 128 + m * 16; float ss = 0.f;
; #pragma unroll
;                 for (int bj = 0; bj < 2; ++bj) {
;                     const size_t off = (size_t)row * DM + col0 + bj * 128;
;                     const v4u b = *(const v4u*)(xb + off);
;                     f32x4 v0, v1; v0[0] = bflo(b.x); v0[1] = bfhi(b.x); v0[2] = bflo(b.y); v0[3] = bfhi(b.y); v1[0] = bflo(b.z); v1[1] = bfhi(b.z); v1[2] = bflo(b.w); v1[3] = bfhi(b.w);
;                     v0 = v0 + alpha * acc[ai][bj][m][0]; v1 = v1 + alpha * acc[ai][bj][m][1];
;                     const v4u w = pack8(v0, v1); *(v4u*)(xb + off) = w;
;                     const float r0 = bflo(w.x), r1 = bfhi(w.x), r2 = bflo(w.y), r3 = bfhi(w.y), r4 = bflo(w.z), r5 = bfhi(w.z), r6 = bflo(w.w), r7 = bfhi(w.w);
;                     ss += (r0 * r0 + r1 * r1) + (r2 * r2 + r3 * r3) + (r4 * r4 + r5 * r5) + (r6 * r6 + r7 * r7);
;                 }
;                 ss += __shfl_xor(ss, 16); ss += __shfl_xor(ss, 32);
;                 if (fq == 0) ssq[(size_t)row * 16 + u.pn * 4 + wc] = ss;
.LBB0_281:
	v_and_b32_e32 v142, 64, v215
	v_xor_b32_e32 v141, 16, v215
	v_add_u32_e32 v142, 64, v142
	v_cmp_lt_i32_e32 vcc, v141, v142
	v_lshl_add_u32 v140, s68, 8, v144
	v_lshl_or_b32 v138, s34, 8, v146
	v_cndmask_b32_e32 v141, v215, v141, vcc
	v_lshlrev_b32_e32 v148, 2, v141
	v_xor_b32_e32 v141, 32, v215
	v_cmp_lt_i32_e32 vcc, v141, v142
	v_ashrrev_i32_e32 v139, 31, v138
	s_nop 0
	v_cndmask_b32_e32 v141, v215, v141, vcc
	v_lshlrev_b32_e32 v149, 2, v141
	v_ashrrev_i32_e32 v141, 31, v140
	v_lshlrev_b64 v[142:143], 11, v[140:141]
	v_lshl_add_u64 v[142:143], s[12:13], 0, v[142:143]
	v_lshl_add_u64 v[142:143], v[138:139], 1, v[142:143]
	s_waitcnt vmcnt(15)
	v_lshlrev_b32_e32 v154, 16, v160
	v_and_b32_e32 v155, 0xffff0000, v160
	v_lshlrev_b32_e32 v150, 16, v161
	v_and_b32_e32 v151, 0xffff0000, v161
	v_lshlrev_b32_e32 v156, 16, v162
	v_and_b32_e32 v157, 0xffff0000, v162
	v_lshlrev_b32_e32 v152, 16, v163
	v_and_b32_e32 v153, 0xffff0000, v163
	v_pk_fma_f32 v[126:127], v[126:127], 0.5, v[150:151] op_sel_hi:[1,0,1]
	v_pk_fma_f32 v[124:125], v[124:125], 0.5, v[154:155] op_sel_hi:[1,0,1]
	v_pk_fma_f32 v[150:151], v[122:123], 0.5, v[152:153] op_sel_hi:[1,0,1]
	v_pk_fma_f32 v[122:123], v[120:121], 0.5, v[156:157] op_sel_hi:[1,0,1]
	v_cvt_pk_bf16_f32 v120, v124, v125
	v_cvt_pk_bf16_f32 v121, v126, v127
	v_cvt_pk_bf16_f32 v122, v122, v123
	v_cvt_pk_bf16_f32 v123, v150, v151
	global_store_dwordx4 v[142:143], v[120:123], off
	v_lshlrev_b32_e32 v124, 16, v120
	v_lshlrev_b32_e32 v125, 16, v121
	v_and_b32_e32 v120, 0xffff0000, v120
	v_and_b32_e32 v121, 0xffff0000, v121
	v_mul_f32_e32 v120, v120, v120
	v_mul_f32_e32 v121, v121, v121
	v_lshlrev_b32_e32 v126, 16, v122
	v_and_b32_e32 v122, 0xffff0000, v122
	v_fmac_f32_e32 v120, v124, v124
	v_fmac_f32_e32 v121, v125, v125
	v_add_f32_e32 v120, v120, v121
	v_mul_f32_e32 v121, v122, v122
	v_lshlrev_b32_e32 v127, 16, v123
	v_and_b32_e32 v123, 0xffff0000, v123
	v_fmac_f32_e32 v121, v126, v126
	v_add_f32_e32 v120, v121, v120
	v_mul_f32_e32 v121, v123, v123
	v_fmac_f32_e32 v121, v127, v127
	v_add_f32_e32 v150, v121, v120
	s_waitcnt vmcnt(15)
	v_lshlrev_b32_e32 v124, 16, v164
	v_and_b32_e32 v125, 0xffff0000, v164
	v_lshlrev_b32_e32 v120, 16, v165
	v_and_b32_e32 v121, 0xffff0000, v165
	v_lshlrev_b32_e32 v126, 16, v166
	v_and_b32_e32 v127, 0xffff0000, v166
	v_lshlrev_b32_e32 v122, 16, v167
	v_and_b32_e32 v123, 0xffff0000, v167
	v_pk_fma_f32 v[118:119], v[118:119], 0.5, v[120:121] op_sel_hi:[1,0,1]
	v_pk_fma_f32 v[116:117], v[116:117], 0.5, v[124:125] op_sel_hi:[1,0,1]
	v_pk_fma_f32 v[120:121], v[114:115], 0.5, v[122:123] op_sel_hi:[1,0,1]
	v_pk_fma_f32 v[114:115], v[112:113], 0.5, v[126:127] op_sel_hi:[1,0,1]
	v_cvt_pk_bf16_f32 v112, v116, v117
	v_cvt_pk_bf16_f32 v113, v118, v119
	v_cvt_pk_bf16_f32 v114, v114, v115
	v_cvt_pk_bf16_f32 v115, v120, v121
	global_store_dwordx4 v[142:143], v[112:115], off offset:256
	v_lshlrev_b32_e32 v116, 16, v112
	v_lshlrev_b32_e32 v117, 16, v113
	v_and_b32_e32 v112, 0xffff0000, v112
	v_and_b32_e32 v113, 0xffff0000, v113
	v_mul_f32_e32 v112, v112, v112
	v_mul_f32_e32 v113, v113, v113
	v_lshlrev_b32_e32 v118, 16, v114
	v_and_b32_e32 v114, 0xffff0000, v114
	v_fmac_f32_e32 v112, v116, v116
	v_fmac_f32_e32 v113, v117, v117
	v_add_f32_e32 v112, v112, v113
	v_mul_f32_e32 v113, v114, v114
	v_lshlrev_b32_e32 v119, 16, v115
	v_and_b32_e32 v115, 0xffff0000, v115
	v_fmac_f32_e32 v113, v118, v118
	v_add_f32_e32 v112, v113, v112
	v_mul_f32_e32 v113, v115, v115
	v_fmac_f32_e32 v113, v119, v119
	v_add_f32_e32 v112, v113, v112
	v_add_f32_e32 v112, v150, v112
	v_mov_b32_e32 v113, v112
	s_nop 1
	v_permlane16_swap_b32_e32 v112, v113
	s_waitcnt lgkmcnt(0)
	v_add_f32_e32 v112, v112, v113
	v_mov_b32_e32 v113, v112
	s_nop 1
	v_permlane32_swap_b32_e32 v112, v113
	s_and_saveexec_b64 s[20:21], s[4:5]
	s_cbranch_execz .LBB0_283
	s_waitcnt lgkmcnt(0)
	v_add_f32_e32 v114, v112, v113
	s_lshl_b32 s22, s34, 2
	v_lshlrev_b64 v[112:113], 6, v[140:141]
	s_ashr_i32 s23, s22, 31
	v_lshl_add_u64 v[112:113], s[14:15], 0, v[112:113]
	v_lshl_add_u64 v[112:113], s[22:23], 2, v[112:113]
	s_lshl_b32 s68, s45, 2
	v_lshl_add_u64 v[112:113], v[112:113], 0, s[68:69]
	global_store_dword v[112:113], v114, off
.LBB0_283:
	s_or_b64 exec, exec, s[20:21]
	v_or_b32_e32 v112, 16, v140
	s_waitcnt lgkmcnt(0)
	v_ashrrev_i32_e32 v113, 31, v112
	v_lshlrev_b64 v[114:115], 11, v[112:113]
	v_lshl_add_u64 v[114:115], s[12:13], 0, v[114:115]
	v_lshl_add_u64 v[114:115], v[138:139], 1, v[114:115]
	s_waitcnt vmcnt(15)
	v_lshlrev_b32_e32 v120, 16, v168
	v_and_b32_e32 v121, 0xffff0000, v168
	v_lshlrev_b32_e32 v116, 16, v169
	v_and_b32_e32 v117, 0xffff0000, v169
	v_lshlrev_b32_e32 v122, 16, v170
	v_and_b32_e32 v123, 0xffff0000, v170
	v_lshlrev_b32_e32 v118, 16, v171
	v_and_b32_e32 v119, 0xffff0000, v171
	v_pk_fma_f32 v[110:111], v[110:111], 0.5, v[116:117] op_sel_hi:[1,0,1]
	v_pk_fma_f32 v[108:109], v[108:109], 0.5, v[120:121] op_sel_hi:[1,0,1]
	v_pk_fma_f32 v[116:117], v[106:107], 0.5, v[118:119] op_sel_hi:[1,0,1]
	v_pk_fma_f32 v[106:107], v[104:105], 0.5, v[122:123] op_sel_hi:[1,0,1]
	v_cvt_pk_bf16_f32 v104, v108, v109
	v_cvt_pk_bf16_f32 v105, v110, v111
	v_cvt_pk_bf16_f32 v106, v106, v107
	v_cvt_pk_bf16_f32 v107, v116, v117
	global_store_dwordx4 v[114:115], v[104:107], off
	v_lshlrev_b32_e32 v108, 16, v104
	v_lshlrev_b32_e32 v109, 16, v105
	v_and_b32_e32 v104, 0xffff0000, v104
	v_and_b32_e32 v105, 0xffff0000, v105
	v_mul_f32_e32 v104, v104, v104
	v_mul_f32_e32 v105, v105, v105
	v_lshlrev_b32_e32 v110, 16, v106
	v_and_b32_e32 v106, 0xffff0000, v106
	v_fmac_f32_e32 v104, v108, v108
	v_fmac_f32_e32 v105, v109, v109
	v_add_f32_e32 v104, v104, v105
	v_mul_f32_e32 v105, v106, v106
	v_lshlrev_b32_e32 v111, 16, v107
	v_and_b32_e32 v107, 0xffff0000, v107
	v_fmac_f32_e32 v105, v110, v110
	v_add_f32_e32 v104, v105, v104
	v_mul_f32_e32 v105, v107, v107
	v_fmac_f32_e32 v105, v111, v111
	v_add_f32_e32 v116, v105, v104
	s_waitcnt vmcnt(15)
; __device__ __forceinline__ float bflo(unsigned w) { return __uint_as_float(w << 16); }
; __device__ __forceinline__ float bfhi(unsigned w) { return __uint_as_float(w & 0xffff0000u); }
; __device__ __forceinline__ v4u pack8(const f32x4 a, const f32x4 b) { v4u w; w.x = cvt_pk_bf16(a[0], a[1]); w.y = cvt_pk_bf16(a[2], a[3]); w.z = cvt_pk_bf16(b[0], b[1]); w.w = cvt_pk_bf16(b[2], b[3]); return w; }
;     __device__ __forceinline__ void operator()(const f32x4 (&acc)[2][2][4][2], const pg8::Unit& u, int wr, int wc, int fr, int fq) const {
;     ...
;                 const int row = row0 + ai * 128 + m * 16; float ss = 0.f;
; #pragma unroll
;                 for (int bj = 0; bj < 2; ++bj) {
;                     const size_t off = (size_t)row * DM + col0 + bj * 128;
;                     const v4u b = *(const v4u*)(xb + off);
;                     f32x4 v0, v1; v0[0] = bflo(b.x); v0[1] = bfhi(b.x); v0[2] = bflo(b.y); v0[3] = bfhi(b.y); v1[0] = bflo(b.z); v1[1] = bfhi(b.z); v1[2] = bflo(b.w); v1[3] = bfhi(b.w);
;                     v0 = v0 + alpha * acc[ai][bj][m][0]; v1 = v1 + alpha * acc[ai][bj][m][1];
;                     const v4u w = pack8(v0, v1); *(v4u*)(xb + off) = w;
;                     const float r0 = bflo(w.x), r1 = bfhi(w.x), r2 = bflo(w.y), r3 = bfhi(w.y), r4 = bflo(w.z), r5 = bfhi(w.z), r6 = bflo(w.w), r7 = bfhi(w.w);
;                     ss += (r0 * r0 + r1 * r1) + (r2 * r2 + r3 * r3) + (r4 * r4 + r5 * r5) + (r6 * r6 + r7 * r7);
;                 }
;                 ss += __shfl_xor(ss, 16); ss += __shfl_xor(ss, 32);
;                 if (fq == 0) ssq[(size_t)row * 16 + u.pn * 4 + wc] = ss;
	v_lshlrev_b32_e32 v108, 16, v172
	v_and_b32_e32 v109, 0xffff0000, v172
	v_lshlrev_b32_e32 v104, 16, v173
	v_and_b32_e32 v105, 0xffff0000, v173
	v_lshlrev_b32_e32 v110, 16, v174
	v_and_b32_e32 v111, 0xffff0000, v174
	v_lshlrev_b32_e32 v106, 16, v175
	v_and_b32_e32 v107, 0xffff0000, v175
	v_pk_fma_f32 v[102:103], v[102:103], 0.5, v[104:105] op_sel_hi:[1,0,1]
	v_pk_fma_f32 v[100:101], v[100:101], 0.5, v[108:109] op_sel_hi:[1,0,1]
	v_pk_fma_f32 v[104:105], v[98:99], 0.5, v[106:107] op_sel_hi:[1,0,1]
	v_pk_fma_f32 v[98:99], v[96:97], 0.5, v[110:111] op_sel_hi:[1,0,1]
	v_cvt_pk_bf16_f32 v96, v100, v101
	v_cvt_pk_bf16_f32 v97, v102, v103
	v_cvt_pk_bf16_f32 v98, v98, v99
	v_cvt_pk_bf16_f32 v99, v104, v105
	global_store_dwordx4 v[114:115], v[96:99], off offset:256
	v_lshlrev_b32_e32 v100, 16, v96
	v_lshlrev_b32_e32 v101, 16, v97
	v_and_b32_e32 v96, 0xffff0000, v96
	v_and_b32_e32 v97, 0xffff0000, v97
	v_mul_f32_e32 v96, v96, v96
	v_mul_f32_e32 v97, v97, v97
	v_lshlrev_b32_e32 v102, 16, v98
	v_and_b32_e32 v98, 0xffff0000, v98
	v_fmac_f32_e32 v96, v100, v100
	v_fmac_f32_e32 v97, v101, v101
	v_add_f32_e32 v96, v96, v97
	v_mul_f32_e32 v97, v98, v98
	v_lshlrev_b32_e32 v103, 16, v99
	v_and_b32_e32 v99, 0xffff0000, v99
	v_fmac_f32_e32 v97, v102, v102
	v_add_f32_e32 v96, v97, v96
	v_mul_f32_e32 v97, v99, v99
	v_fmac_f32_e32 v97, v103, v103
	v_add_f32_e32 v96, v97, v96
	v_add_f32_e32 v96, v116, v96
	v_mov_b32_e32 v97, v96
	s_nop 1
	v_permlane16_swap_b32_e32 v96, v97
	s_waitcnt lgkmcnt(0)
	v_add_f32_e32 v96, v96, v97
	v_mov_b32_e32 v97, v96
	s_nop 1
	v_permlane32_swap_b32_e32 v96, v97
	s_and_saveexec_b64 s[20:21], s[4:5]
	s_cbranch_execz .LBB0_285
	s_waitcnt lgkmcnt(0)
	v_add_f32_e32 v98, v96, v97
	s_lshl_b32 s22, s34, 2
	v_lshlrev_b64 v[96:97], 6, v[112:113]
	s_ashr_i32 s23, s22, 31
	v_lshl_add_u64 v[96:97], s[14:15], 0, v[96:97]
	v_lshl_add_u64 v[96:97], s[22:23], 2, v[96:97]
	s_lshl_b32 s68, s45, 2
	v_lshl_add_u64 v[96:97], v[96:97], 0, s[68:69]
	global_store_dword v[96:97], v98, off
.LBB0_285:
	s_or_b64 exec, exec, s[20:21]
	v_or_b32_e32 v96, 32, v140
	s_waitcnt lgkmcnt(0)
	v_ashrrev_i32_e32 v97, 31, v96
	v_lshlrev_b64 v[98:99], 11, v[96:97]
	v_lshl_add_u64 v[98:99], s[12:13], 0, v[98:99]
	v_lshl_add_u64 v[98:99], v[138:139], 1, v[98:99]
	s_waitcnt vmcnt(15)
	v_lshlrev_b32_e32 v104, 16, v176
	v_and_b32_e32 v105, 0xffff0000, v176
	v_lshlrev_b32_e32 v100, 16, v177
	v_and_b32_e32 v101, 0xffff0000, v177
	v_lshlrev_b32_e32 v106, 16, v178
	v_and_b32_e32 v107, 0xffff0000, v178
	v_lshlrev_b32_e32 v102, 16, v179
	v_and_b32_e32 v103, 0xffff0000, v179
	v_pk_fma_f32 v[94:95], v[94:95], 0.5, v[100:101] op_sel_hi:[1,0,1]
	v_pk_fma_f32 v[92:93], v[92:93], 0.5, v[104:105] op_sel_hi:[1,0,1]
	v_pk_fma_f32 v[100:101], v[90:91], 0.5, v[102:103] op_sel_hi:[1,0,1]
	v_pk_fma_f32 v[90:91], v[88:89], 0.5, v[106:107] op_sel_hi:[1,0,1]
	v_cvt_pk_bf16_f32 v88, v92, v93
	v_cvt_pk_bf16_f32 v89, v94, v95
	v_cvt_pk_bf16_f32 v90, v90, v91
	v_cvt_pk_bf16_f32 v91, v100, v101
	global_store_dwordx4 v[98:99], v[88:91], off
	v_lshlrev_b32_e32 v92, 16, v88
	v_lshlrev_b32_e32 v93, 16, v89
	v_and_b32_e32 v88, 0xffff0000, v88
	v_and_b32_e32 v89, 0xffff0000, v89
	v_mul_f32_e32 v88, v88, v88
	v_mul_f32_e32 v89, v89, v89
	v_lshlrev_b32_e32 v94, 16, v90
	v_and_b32_e32 v90, 0xffff0000, v90
	v_fmac_f32_e32 v88, v92, v92
	v_fmac_f32_e32 v89, v93, v93
	v_add_f32_e32 v88, v88, v89
	v_mul_f32_e32 v89, v90, v90
	v_lshlrev_b32_e32 v95, 16, v91
	v_and_b32_e32 v91, 0xffff0000, v91
	v_fmac_f32_e32 v89, v94, v94
	v_add_f32_e32 v88, v89, v88
	v_mul_f32_e32 v89, v91, v91
	v_fmac_f32_e32 v89, v95, v95
	v_add_f32_e32 v100, v89, v88
	s_waitcnt vmcnt(15)
	v_lshlrev_b32_e32 v92, 16, v180
	v_and_b32_e32 v93, 0xffff0000, v180
	v_lshlrev_b32_e32 v88, 16, v181
	v_and_b32_e32 v89, 0xffff0000, v181
	v_lshlrev_b32_e32 v94, 16, v182
	v_and_b32_e32 v95, 0xffff0000, v182
	v_lshlrev_b32_e32 v90, 16, v183
	v_and_b32_e32 v91, 0xffff0000, v183
	v_pk_fma_f32 v[86:87], v[86:87], 0.5, v[88:89] op_sel_hi:[1,0,1]
	v_pk_fma_f32 v[84:85], v[84:85], 0.5, v[92:93] op_sel_hi:[1,0,1]
	v_pk_fma_f32 v[88:89], v[82:83], 0.5, v[90:91] op_sel_hi:[1,0,1]
	v_pk_fma_f32 v[82:83], v[80:81], 0.5, v[94:95] op_sel_hi:[1,0,1]
	v_cvt_pk_bf16_f32 v80, v84, v85
	v_cvt_pk_bf16_f32 v81, v86, v87
	v_cvt_pk_bf16_f32 v82, v82, v83
	v_cvt_pk_bf16_f32 v83, v88, v89
	global_store_dwordx4 v[98:99], v[80:83], off offset:256
	v_lshlrev_b32_e32 v84, 16, v80
	v_lshlrev_b32_e32 v85, 16, v81
	v_and_b32_e32 v80, 0xffff0000, v80
	v_and_b32_e32 v81, 0xffff0000, v81
	v_mul_f32_e32 v80, v80, v80
	v_mul_f32_e32 v81, v81, v81
	v_lshlrev_b32_e32 v86, 16, v82
	v_and_b32_e32 v82, 0xffff0000, v82
	v_fmac_f32_e32 v80, v84, v84
	v_fmac_f32_e32 v81, v85, v85
	v_add_f32_e32 v80, v80, v81
	v_mul_f32_e32 v81, v82, v82
	v_lshlrev_b32_e32 v87, 16, v83
	v_and_b32_e32 v83, 0xffff0000, v83
	v_fmac_f32_e32 v81, v86, v86
	v_add_f32_e32 v80, v81, v80
	v_mul_f32_e32 v81, v83, v83
	v_fmac_f32_e32 v81, v87, v87
	v_add_f32_e32 v80, v81, v80
	v_add_f32_e32 v80, v100, v80
	v_mov_b32_e32 v81, v80
	s_nop 1
	v_permlane16_swap_b32_e32 v80, v81
	s_waitcnt lgkmcnt(0)
	v_add_f32_e32 v80, v80, v81
	v_mov_b32_e32 v81, v80
	s_nop 1
	v_permlane32_swap_b32_e32 v80, v81
	s_and_saveexec_b64 s[20:21], s[4:5]
	s_cbranch_execz .LBB0_287
	s_waitcnt lgkmcnt(0)
	v_add_f32_e32 v82, v80, v81
	s_lshl_b32 s22, s34, 2
	v_lshlrev_b64 v[80:81], 6, v[96:97]
	s_ashr_i32 s23, s22, 31
	v_lshl_add_u64 v[80:81], s[14:15], 0, v[80:81]
	v_lshl_add_u64 v[80:81], s[22:23], 2, v[80:81]
	s_lshl_b32 s68, s45, 2
	v_lshl_add_u64 v[80:81], v[80:81], 0, s[68:69]
	global_store_dword v[80:81], v82, off
; __device__ __forceinline__ float bflo(unsigned w) { return __uint_as_float(w << 16); }
; __device__ __forceinline__ float bfhi(unsigned w) { return __uint_as_float(w & 0xffff0000u); }
; __device__ __forceinline__ v4u pack8(const f32x4 a, const f32x4 b) { v4u w; w.x = cvt_pk_bf16(a[0], a[1]); w.y = cvt_pk_bf16(a[2], a[3]); w.z = cvt_pk_bf16(b[0], b[1]); w.w = cvt_pk_bf16(b[2], b[3]); return w; }
;     __device__ __forceinline__ void operator()(const f32x4 (&acc)[2][2][4][2], const pg8::Unit& u, int wr, int wc, int fr, int fq) const {
;     ...
;                 const int row = row0 + ai * 128 + m * 16; float ss = 0.f;
; #pragma unroll
;                 for (int bj = 0; bj < 2; ++bj) {
;                     const size_t off = (size_t)row * DM + col0 + bj * 128;
;                     const v4u b = *(const v4u*)(xb + off);
;                     f32x4 v0, v1; v0[0] = bflo(b.x); v0[1] = bfhi(b.x); v0[2] = bflo(b.y); v0[3] = bfhi(b.y); v1[0] = bflo(b.z); v1[1] = bfhi(b.z); v1[2] = bflo(b.w); v1[3] = bfhi(b.w);
;                     v0 = v0 + alpha * acc[ai][bj][m][0]; v1 = v1 + alpha * acc[ai][bj][m][1];
;                     const v4u w = pack8(v0, v1); *(v4u*)(xb + off) = w;
;                     const float r0 = bflo(w.x), r1 = bfhi(w.x), r2 = bflo(w.y), r3 = bfhi(w.y), r4 = bflo(w.z), r5 = bfhi(w.z), r6 = bflo(w.w), r7 = bfhi(w.w);
;                     ss += (r0 * r0 + r1 * r1) + (r2 * r2 + r3 * r3) + (r4 * r4 + r5 * r5) + (r6 * r6 + r7 * r7);
;                 }
;                 ss += __shfl_xor(ss, 16); ss += __shfl_xor(ss, 32);
;                 if (fq == 0) ssq[(size_t)row * 16 + u.pn * 4 + wc] = ss;
.LBB0_287:
	s_or_b64 exec, exec, s[20:21]
	v_or_b32_e32 v80, 48, v140
	s_waitcnt lgkmcnt(0)
	v_ashrrev_i32_e32 v81, 31, v80
	v_lshlrev_b64 v[82:83], 11, v[80:81]
	v_lshl_add_u64 v[82:83], s[12:13], 0, v[82:83]
	v_lshl_add_u64 v[82:83], v[138:139], 1, v[82:83]
	s_waitcnt vmcnt(15)
	v_lshlrev_b32_e32 v88, 16, v184
	v_and_b32_e32 v89, 0xffff0000, v184
	v_lshlrev_b32_e32 v84, 16, v185
	v_and_b32_e32 v85, 0xffff0000, v185
	v_lshlrev_b32_e32 v90, 16, v186
	v_and_b32_e32 v91, 0xffff0000, v186
	v_lshlrev_b32_e32 v86, 16, v187
	v_and_b32_e32 v87, 0xffff0000, v187
	v_pk_fma_f32 v[78:79], v[78:79], 0.5, v[84:85] op_sel_hi:[1,0,1]
	v_pk_fma_f32 v[76:77], v[76:77], 0.5, v[88:89] op_sel_hi:[1,0,1]
	v_pk_fma_f32 v[84:85], v[74:75], 0.5, v[86:87] op_sel_hi:[1,0,1]
	v_pk_fma_f32 v[74:75], v[72:73], 0.5, v[90:91] op_sel_hi:[1,0,1]
	v_cvt_pk_bf16_f32 v72, v76, v77
	v_cvt_pk_bf16_f32 v73, v78, v79
	v_cvt_pk_bf16_f32 v74, v74, v75
	v_cvt_pk_bf16_f32 v75, v84, v85
	global_store_dwordx4 v[82:83], v[72:75], off
	v_lshlrev_b32_e32 v76, 16, v72
	v_lshlrev_b32_e32 v77, 16, v73
	v_and_b32_e32 v72, 0xffff0000, v72
	v_and_b32_e32 v73, 0xffff0000, v73
	v_mul_f32_e32 v72, v72, v72
	v_mul_f32_e32 v73, v73, v73
	v_lshlrev_b32_e32 v78, 16, v74
	v_and_b32_e32 v74, 0xffff0000, v74
	v_fmac_f32_e32 v72, v76, v76
	v_fmac_f32_e32 v73, v77, v77
	v_add_f32_e32 v72, v72, v73
	v_mul_f32_e32 v73, v74, v74
	v_lshlrev_b32_e32 v79, 16, v75
	v_and_b32_e32 v75, 0xffff0000, v75
	v_fmac_f32_e32 v73, v78, v78
	v_add_f32_e32 v72, v73, v72
	v_mul_f32_e32 v73, v75, v75
	v_fmac_f32_e32 v73, v79, v79
	v_add_f32_e32 v84, v73, v72
	s_waitcnt vmcnt(15)
	v_lshlrev_b32_e32 v76, 16, v188
	v_and_b32_e32 v77, 0xffff0000, v188
	v_lshlrev_b32_e32 v72, 16, v189
	v_and_b32_e32 v73, 0xffff0000, v189
	v_lshlrev_b32_e32 v78, 16, v190
	v_and_b32_e32 v79, 0xffff0000, v190
	v_lshlrev_b32_e32 v74, 16, v191
	v_and_b32_e32 v75, 0xffff0000, v191
	v_pk_fma_f32 v[70:71], v[70:71], 0.5, v[72:73] op_sel_hi:[1,0,1]
	v_pk_fma_f32 v[68:69], v[68:69], 0.5, v[76:77] op_sel_hi:[1,0,1]
	v_pk_fma_f32 v[72:73], v[66:67], 0.5, v[74:75] op_sel_hi:[1,0,1]
	v_pk_fma_f32 v[66:67], v[64:65], 0.5, v[78:79] op_sel_hi:[1,0,1]
	v_cvt_pk_bf16_f32 v64, v68, v69
	v_cvt_pk_bf16_f32 v65, v70, v71
	v_cvt_pk_bf16_f32 v66, v66, v67
	v_cvt_pk_bf16_f32 v67, v72, v73
	global_store_dwordx4 v[82:83], v[64:67], off offset:256
	v_lshlrev_b32_e32 v68, 16, v64
	v_lshlrev_b32_e32 v69, 16, v65
	v_and_b32_e32 v64, 0xffff0000, v64
	v_and_b32_e32 v65, 0xffff0000, v65
	v_mul_f32_e32 v64, v64, v64
	v_mul_f32_e32 v65, v65, v65
	v_lshlrev_b32_e32 v70, 16, v66
	v_and_b32_e32 v66, 0xffff0000, v66
	v_fmac_f32_e32 v64, v68, v68
	v_fmac_f32_e32 v65, v69, v69
	v_add_f32_e32 v64, v64, v65
	v_mul_f32_e32 v65, v66, v66
	v_lshlrev_b32_e32 v71, 16, v67
	v_and_b32_e32 v67, 0xffff0000, v67
	v_fmac_f32_e32 v65, v70, v70
	v_add_f32_e32 v64, v65, v64
	v_mul_f32_e32 v65, v67, v67
	v_fmac_f32_e32 v65, v71, v71
	v_add_f32_e32 v64, v65, v64
	v_add_f32_e32 v64, v84, v64
	v_mov_b32_e32 v65, v64
	s_nop 1
	v_permlane16_swap_b32_e32 v64, v65
	s_waitcnt lgkmcnt(0)
	v_add_f32_e32 v64, v64, v65
	v_mov_b32_e32 v65, v64
	s_nop 1
	v_permlane32_swap_b32_e32 v64, v65
	s_and_saveexec_b64 s[20:21], s[4:5]
	s_cbranch_execz .LBB0_289
	s_waitcnt lgkmcnt(0)
	v_add_f32_e32 v66, v64, v65
	s_lshl_b32 s22, s34, 2
	v_lshlrev_b64 v[64:65], 6, v[80:81]
	s_ashr_i32 s23, s22, 31
	v_lshl_add_u64 v[64:65], s[14:15], 0, v[64:65]
	v_lshl_add_u64 v[64:65], s[22:23], 2, v[64:65]
	s_lshl_b32 s68, s45, 2
	v_lshl_add_u64 v[64:65], v[64:65], 0, s[68:69]
	global_store_dword v[64:65], v66, off
.LBB0_289:
	s_or_b64 exec, exec, s[20:21]
	v_add_u32_e32 v64, 0x80, v140
	s_waitcnt lgkmcnt(0)
	v_ashrrev_i32_e32 v65, 31, v64
	v_lshlrev_b64 v[66:67], 11, v[64:65]
	v_lshl_add_u64 v[66:67], s[12:13], 0, v[66:67]
	v_lshl_add_u64 v[66:67], v[138:139], 1, v[66:67]
	s_waitcnt vmcnt(15)
	v_lshlrev_b32_e32 v72, 16, v204
	v_and_b32_e32 v73, 0xffff0000, v204
	v_lshlrev_b32_e32 v68, 16, v205
	v_and_b32_e32 v69, 0xffff0000, v205
	v_lshlrev_b32_e32 v74, 16, v206
	v_and_b32_e32 v75, 0xffff0000, v206
	v_lshlrev_b32_e32 v70, 16, v207
	v_and_b32_e32 v71, 0xffff0000, v207
	v_pk_fma_f32 v[62:63], v[62:63], 0.5, v[68:69] op_sel_hi:[1,0,1]
	v_pk_fma_f32 v[60:61], v[60:61], 0.5, v[72:73] op_sel_hi:[1,0,1]
	v_pk_fma_f32 v[68:69], v[58:59], 0.5, v[70:71] op_sel_hi:[1,0,1]
	v_pk_fma_f32 v[58:59], v[56:57], 0.5, v[74:75] op_sel_hi:[1,0,1]
	v_cvt_pk_bf16_f32 v56, v60, v61
	v_cvt_pk_bf16_f32 v57, v62, v63
	v_cvt_pk_bf16_f32 v58, v58, v59
	v_cvt_pk_bf16_f32 v59, v68, v69
	global_store_dwordx4 v[66:67], v[56:59], off
	v_lshlrev_b32_e32 v60, 16, v56
	v_lshlrev_b32_e32 v61, 16, v57
	v_and_b32_e32 v56, 0xffff0000, v56
	v_and_b32_e32 v57, 0xffff0000, v57
	v_mul_f32_e32 v56, v56, v56
	v_mul_f32_e32 v57, v57, v57
	v_lshlrev_b32_e32 v62, 16, v58
	v_and_b32_e32 v58, 0xffff0000, v58
	v_fmac_f32_e32 v56, v60, v60
	v_fmac_f32_e32 v57, v61, v61
	v_add_f32_e32 v56, v56, v57
	v_mul_f32_e32 v57, v58, v58
	v_lshlrev_b32_e32 v63, 16, v59
	v_and_b32_e32 v59, 0xffff0000, v59
	v_fmac_f32_e32 v57, v62, v62
	v_add_f32_e32 v56, v57, v56
	v_mul_f32_e32 v57, v59, v59
	v_fmac_f32_e32 v57, v63, v63
	v_add_f32_e32 v68, v57, v56
	s_waitcnt vmcnt(15)
	v_lshlrev_b32_e32 v60, 16, v208
	v_and_b32_e32 v61, 0xffff0000, v208
	v_lshlrev_b32_e32 v56, 16, v209
	v_and_b32_e32 v57, 0xffff0000, v209
	v_lshlrev_b32_e32 v62, 16, v210
	v_and_b32_e32 v63, 0xffff0000, v210
	v_lshlrev_b32_e32 v58, 16, v211
	v_and_b32_e32 v59, 0xffff0000, v211
	v_pk_fma_f32 v[54:55], v[54:55], 0.5, v[56:57] op_sel_hi:[1,0,1]
	v_pk_fma_f32 v[52:53], v[52:53], 0.5, v[60:61] op_sel_hi:[1,0,1]
	v_pk_fma_f32 v[56:57], v[50:51], 0.5, v[58:59] op_sel_hi:[1,0,1]
	v_pk_fma_f32 v[50:51], v[48:49], 0.5, v[62:63] op_sel_hi:[1,0,1]
	v_cvt_pk_bf16_f32 v48, v52, v53
	v_cvt_pk_bf16_f32 v49, v54, v55
	v_cvt_pk_bf16_f32 v50, v50, v51
	v_cvt_pk_bf16_f32 v51, v56, v57
	global_store_dwordx4 v[66:67], v[48:51], off offset:256
	v_lshlrev_b32_e32 v52, 16, v48
	v_lshlrev_b32_e32 v53, 16, v49
	v_and_b32_e32 v48, 0xffff0000, v48
	v_and_b32_e32 v49, 0xffff0000, v49
	v_mul_f32_e32 v48, v48, v48
	v_mul_f32_e32 v49, v49, v49
	v_lshlrev_b32_e32 v54, 16, v50
	v_and_b32_e32 v50, 0xffff0000, v50
	v_fmac_f32_e32 v48, v52, v52
	v_fmac_f32_e32 v49, v53, v53
	v_add_f32_e32 v48, v48, v49
	v_mul_f32_e32 v49, v50, v50
	v_lshlrev_b32_e32 v55, 16, v51
	v_and_b32_e32 v51, 0xffff0000, v51
	v_fmac_f32_e32 v49, v54, v54
	v_add_f32_e32 v48, v49, v48
	v_mul_f32_e32 v49, v51, v51
	v_fmac_f32_e32 v49, v55, v55
	v_add_f32_e32 v48, v49, v48
	v_add_f32_e32 v48, v68, v48
	v_mov_b32_e32 v49, v48
	s_nop 1
	v_permlane16_swap_b32_e32 v48, v49
	s_waitcnt lgkmcnt(0)
	v_add_f32_e32 v48, v48, v49
	v_mov_b32_e32 v49, v48
	s_nop 1
	v_permlane32_swap_b32_e32 v48, v49
	s_and_saveexec_b64 s[20:21], s[4:5]
	s_cbranch_execz .LBB0_291
; __device__ __forceinline__ float bflo(unsigned w) { return __uint_as_float(w << 16); }
; __device__ __forceinline__ float bfhi(unsigned w) { return __uint_as_float(w & 0xffff0000u); }
; __device__ __forceinline__ v4u pack8(const f32x4 a, const f32x4 b) { v4u w; w.x = cvt_pk_bf16(a[0], a[1]); w.y = cvt_pk_bf16(a[2], a[3]); w.z = cvt_pk_bf16(b[0], b[1]); w.w = cvt_pk_bf16(b[2], b[3]); return w; }
;     __device__ __forceinline__ void operator()(const f32x4 (&acc)[2][2][4][2], const pg8::Unit& u, int wr, int wc, int fr, int fq) const {
;     ...
;                 const int row = row0 + ai * 128 + m * 16; float ss = 0.f;
; #pragma unroll
;                 for (int bj = 0; bj < 2; ++bj) {
;                     const size_t off = (size_t)row * DM + col0 + bj * 128;
;                     const v4u b = *(const v4u*)(xb + off);
;                     f32x4 v0, v1; v0[0] = bflo(b.x); v0[1] = bfhi(b.x); v0[2] = bflo(b.y); v0[3] = bfhi(b.y); v1[0] = bflo(b.z); v1[1] = bfhi(b.z); v1[2] = bflo(b.w); v1[3] = bfhi(b.w);
;                     v0 = v0 + alpha * acc[ai][bj][m][0]; v1 = v1 + alpha * acc[ai][bj][m][1];
;                     const v4u w = pack8(v0, v1); *(v4u*)(xb + off) = w;
;                     const float r0 = bflo(w.x), r1 = bfhi(w.x), r2 = bflo(w.y), r3 = bfhi(w.y), r4 = bflo(w.z), r5 = bfhi(w.z), r6 = bflo(w.w), r7 = bfhi(w.w);
;                     ss += (r0 * r0 + r1 * r1) + (r2 * r2 + r3 * r3) + (r4 * r4 + r5 * r5) + (r6 * r6 + r7 * r7);
;                 }
;                 ss += __shfl_xor(ss, 16); ss += __shfl_xor(ss, 32);
;                 if (fq == 0) ssq[(size_t)row * 16 + u.pn * 4 + wc] = ss;
	s_waitcnt lgkmcnt(0)
	v_add_f32_e32 v50, v48, v49
	s_lshl_b32 s22, s34, 2
	v_lshlrev_b64 v[48:49], 6, v[64:65]
	s_ashr_i32 s23, s22, 31
	v_lshl_add_u64 v[48:49], s[14:15], 0, v[48:49]
	v_lshl_add_u64 v[48:49], s[22:23], 2, v[48:49]
	s_lshl_b32 s68, s45, 2
	v_lshl_add_u64 v[48:49], v[48:49], 0, s[68:69]
	global_store_dword v[48:49], v50, off
.LBB0_291:
	s_or_b64 exec, exec, s[20:21]
	v_add_u32_e32 v48, 0x90, v140
	s_waitcnt lgkmcnt(0)
	v_ashrrev_i32_e32 v49, 31, v48
	v_lshlrev_b64 v[50:51], 11, v[48:49]
	v_lshl_add_u64 v[50:51], s[12:13], 0, v[50:51]
	v_lshl_add_u64 v[50:51], v[138:139], 1, v[50:51]
	s_waitcnt vmcnt(15)
	v_lshlrev_b32_e32 v56, 16, v220
	v_and_b32_e32 v57, 0xffff0000, v220
	v_lshlrev_b32_e32 v52, 16, v221
	v_and_b32_e32 v53, 0xffff0000, v221
	v_lshlrev_b32_e32 v58, 16, v222
	v_and_b32_e32 v59, 0xffff0000, v222
	v_lshlrev_b32_e32 v54, 16, v223
	v_and_b32_e32 v55, 0xffff0000, v223
	v_pk_fma_f32 v[46:47], v[46:47], 0.5, v[52:53] op_sel_hi:[1,0,1]
	v_pk_fma_f32 v[44:45], v[44:45], 0.5, v[56:57] op_sel_hi:[1,0,1]
	v_pk_fma_f32 v[52:53], v[42:43], 0.5, v[54:55] op_sel_hi:[1,0,1]
	v_pk_fma_f32 v[42:43], v[40:41], 0.5, v[58:59] op_sel_hi:[1,0,1]
	v_cvt_pk_bf16_f32 v40, v44, v45
	v_cvt_pk_bf16_f32 v41, v46, v47
	v_cvt_pk_bf16_f32 v42, v42, v43
	v_cvt_pk_bf16_f32 v43, v52, v53
	global_store_dwordx4 v[50:51], v[40:43], off
	v_lshlrev_b32_e32 v44, 16, v40
	v_lshlrev_b32_e32 v45, 16, v41
	v_and_b32_e32 v40, 0xffff0000, v40
	v_and_b32_e32 v41, 0xffff0000, v41
	v_mul_f32_e32 v40, v40, v40
	v_mul_f32_e32 v41, v41, v41
	v_lshlrev_b32_e32 v46, 16, v42
	v_and_b32_e32 v42, 0xffff0000, v42
	v_fmac_f32_e32 v40, v44, v44
	v_fmac_f32_e32 v41, v45, v45
	v_add_f32_e32 v40, v40, v41
	v_mul_f32_e32 v41, v42, v42
	v_lshlrev_b32_e32 v47, 16, v43
	v_and_b32_e32 v43, 0xffff0000, v43
	v_fmac_f32_e32 v41, v46, v46
	v_add_f32_e32 v40, v41, v40
	v_mul_f32_e32 v41, v43, v43
	v_fmac_f32_e32 v41, v47, v47
	v_add_f32_e32 v52, v41, v40
	s_waitcnt vmcnt(15)
	v_lshlrev_b32_e32 v44, 16, v224
	v_and_b32_e32 v45, 0xffff0000, v224
	v_lshlrev_b32_e32 v40, 16, v225
	v_and_b32_e32 v41, 0xffff0000, v225
	v_lshlrev_b32_e32 v46, 16, v226
	v_and_b32_e32 v47, 0xffff0000, v226
	v_lshlrev_b32_e32 v42, 16, v227
	v_and_b32_e32 v43, 0xffff0000, v227
	v_pk_fma_f32 v[38:39], v[38:39], 0.5, v[40:41] op_sel_hi:[1,0,1]
	v_pk_fma_f32 v[36:37], v[36:37], 0.5, v[44:45] op_sel_hi:[1,0,1]
	v_pk_fma_f32 v[40:41], v[34:35], 0.5, v[42:43] op_sel_hi:[1,0,1]
	v_pk_fma_f32 v[34:35], v[32:33], 0.5, v[46:47] op_sel_hi:[1,0,1]
	v_cvt_pk_bf16_f32 v32, v36, v37
	v_cvt_pk_bf16_f32 v33, v38, v39
	v_cvt_pk_bf16_f32 v34, v34, v35
	v_cvt_pk_bf16_f32 v35, v40, v41
	global_store_dwordx4 v[50:51], v[32:35], off offset:256
	v_lshlrev_b32_e32 v36, 16, v32
	v_lshlrev_b32_e32 v37, 16, v33
	v_and_b32_e32 v32, 0xffff0000, v32
	v_and_b32_e32 v33, 0xffff0000, v33
	v_mul_f32_e32 v32, v32, v32
	v_mul_f32_e32 v33, v33, v33
	v_lshlrev_b32_e32 v38, 16, v34
	v_and_b32_e32 v34, 0xffff0000, v34
	v_fmac_f32_e32 v32, v36, v36
	v_fmac_f32_e32 v33, v37, v37
	v_add_f32_e32 v32, v32, v33
	v_mul_f32_e32 v33, v34, v34
	v_lshlrev_b32_e32 v39, 16, v35
	v_and_b32_e32 v35, 0xffff0000, v35
	v_fmac_f32_e32 v33, v38, v38
	v_add_f32_e32 v32, v33, v32
	v_mul_f32_e32 v33, v35, v35
	v_fmac_f32_e32 v33, v39, v39
	v_add_f32_e32 v32, v33, v32
	v_add_f32_e32 v32, v52, v32
	v_mov_b32_e32 v33, v32
	s_nop 1
	v_permlane16_swap_b32_e32 v32, v33
	s_waitcnt lgkmcnt(0)
	v_add_f32_e32 v32, v32, v33
	v_mov_b32_e32 v33, v32
	s_nop 1
	v_permlane32_swap_b32_e32 v32, v33
	s_and_saveexec_b64 s[20:21], s[4:5]
	s_cbranch_execz .LBB0_293
	s_waitcnt lgkmcnt(0)
	v_add_f32_e32 v34, v32, v33
	s_lshl_b32 s22, s34, 2
	v_lshlrev_b64 v[32:33], 6, v[48:49]
	s_ashr_i32 s23, s22, 31
	v_lshl_add_u64 v[32:33], s[14:15], 0, v[32:33]
	v_lshl_add_u64 v[32:33], s[22:23], 2, v[32:33]
	s_lshl_b32 s68, s45, 2
	v_lshl_add_u64 v[32:33], v[32:33], 0, s[68:69]
	global_store_dword v[32:33], v34, off
; __device__ __forceinline__ float bflo(unsigned w) { return __uint_as_float(w << 16); }
; __device__ __forceinline__ float bfhi(unsigned w) { return __uint_as_float(w & 0xffff0000u); }
; __device__ __forceinline__ v4u pack8(const f32x4 a, const f32x4 b) { v4u w; w.x = cvt_pk_bf16(a[0], a[1]); w.y = cvt_pk_bf16(a[2], a[3]); w.z = cvt_pk_bf16(b[0], b[1]); w.w = cvt_pk_bf16(b[2], b[3]); return w; }
;     __device__ __forceinline__ void operator()(const f32x4 (&acc)[2][2][4][2], const pg8::Unit& u, int wr, int wc, int fr, int fq) const {
;     ...
;                 const int row = row0 + ai * 128 + m * 16; float ss = 0.f;
; #pragma unroll
;                 for (int bj = 0; bj < 2; ++bj) {
;                     const size_t off = (size_t)row * DM + col0 + bj * 128;
;                     const v4u b = *(const v4u*)(xb + off);
;                     f32x4 v0, v1; v0[0] = bflo(b.x); v0[1] = bfhi(b.x); v0[2] = bflo(b.y); v0[3] = bfhi(b.y); v1[0] = bflo(b.z); v1[1] = bfhi(b.z); v1[2] = bflo(b.w); v1[3] = bfhi(b.w);
;                     v0 = v0 + alpha * acc[ai][bj][m][0]; v1 = v1 + alpha * acc[ai][bj][m][1];
;                     const v4u w = pack8(v0, v1); *(v4u*)(xb + off) = w;
;                     const float r0 = bflo(w.x), r1 = bfhi(w.x), r2 = bflo(w.y), r3 = bfhi(w.y), r4 = bflo(w.z), r5 = bfhi(w.z), r6 = bflo(w.w), r7 = bfhi(w.w);
;                     ss += (r0 * r0 + r1 * r1) + (r2 * r2 + r3 * r3) + (r4 * r4 + r5 * r5) + (r6 * r6 + r7 * r7);
;                 }
;                 ss += __shfl_xor(ss, 16); ss += __shfl_xor(ss, 32);
;                 if (fq == 0) ssq[(size_t)row * 16 + u.pn * 4 + wc] = ss;
.LBB0_293:
	s_or_b64 exec, exec, s[20:21]
	v_add_u32_e32 v32, 0xa0, v140
	s_waitcnt lgkmcnt(0)
	v_ashrrev_i32_e32 v33, 31, v32
	v_lshlrev_b64 v[34:35], 11, v[32:33]
	v_lshl_add_u64 v[34:35], s[12:13], 0, v[34:35]
	v_lshl_add_u64 v[34:35], v[138:139], 1, v[34:35]
	s_waitcnt vmcnt(15)
	v_lshlrev_b32_e32 v40, 16, v228
	v_and_b32_e32 v41, 0xffff0000, v228
	v_lshlrev_b32_e32 v36, 16, v229
	v_and_b32_e32 v37, 0xffff0000, v229
	v_lshlrev_b32_e32 v42, 16, v230
	v_and_b32_e32 v43, 0xffff0000, v230
	v_lshlrev_b32_e32 v38, 16, v231
	v_and_b32_e32 v39, 0xffff0000, v231
	v_pk_fma_f32 v[30:31], v[30:31], 0.5, v[36:37] op_sel_hi:[1,0,1]
	v_pk_fma_f32 v[28:29], v[28:29], 0.5, v[40:41] op_sel_hi:[1,0,1]
	v_pk_fma_f32 v[36:37], v[26:27], 0.5, v[38:39] op_sel_hi:[1,0,1]
	v_pk_fma_f32 v[26:27], v[24:25], 0.5, v[42:43] op_sel_hi:[1,0,1]
	v_cvt_pk_bf16_f32 v24, v28, v29
	v_cvt_pk_bf16_f32 v25, v30, v31
	v_cvt_pk_bf16_f32 v26, v26, v27
	v_cvt_pk_bf16_f32 v27, v36, v37
	global_store_dwordx4 v[34:35], v[24:27], off
	v_lshlrev_b32_e32 v28, 16, v24
	v_lshlrev_b32_e32 v29, 16, v25
	v_and_b32_e32 v24, 0xffff0000, v24
	v_and_b32_e32 v25, 0xffff0000, v25
	v_mul_f32_e32 v24, v24, v24
	v_mul_f32_e32 v25, v25, v25
	v_lshlrev_b32_e32 v30, 16, v26
	v_and_b32_e32 v26, 0xffff0000, v26
	v_fmac_f32_e32 v24, v28, v28
	v_fmac_f32_e32 v25, v29, v29
	v_add_f32_e32 v24, v24, v25
	v_mul_f32_e32 v25, v26, v26
	v_lshlrev_b32_e32 v31, 16, v27
	v_and_b32_e32 v27, 0xffff0000, v27
	v_fmac_f32_e32 v25, v30, v30
	v_add_f32_e32 v24, v25, v24
	v_mul_f32_e32 v25, v27, v27
	v_fmac_f32_e32 v25, v31, v31
	v_add_f32_e32 v36, v25, v24
	s_waitcnt vmcnt(15)
	v_lshlrev_b32_e32 v28, 16, v232
	v_and_b32_e32 v29, 0xffff0000, v232
	v_lshlrev_b32_e32 v24, 16, v233
	v_and_b32_e32 v25, 0xffff0000, v233
	v_lshlrev_b32_e32 v30, 16, v234
	v_and_b32_e32 v31, 0xffff0000, v234
	v_lshlrev_b32_e32 v26, 16, v235
	v_and_b32_e32 v27, 0xffff0000, v235
	v_pk_fma_f32 v[22:23], v[22:23], 0.5, v[24:25] op_sel_hi:[1,0,1]
	v_pk_fma_f32 v[20:21], v[20:21], 0.5, v[28:29] op_sel_hi:[1,0,1]
	v_pk_fma_f32 v[24:25], v[18:19], 0.5, v[26:27] op_sel_hi:[1,0,1]
	v_pk_fma_f32 v[18:19], v[16:17], 0.5, v[30:31] op_sel_hi:[1,0,1]
	v_cvt_pk_bf16_f32 v16, v20, v21
	v_cvt_pk_bf16_f32 v17, v22, v23
	v_cvt_pk_bf16_f32 v18, v18, v19
	v_cvt_pk_bf16_f32 v19, v24, v25
	global_store_dwordx4 v[34:35], v[16:19], off offset:256
	v_lshlrev_b32_e32 v20, 16, v16
	v_lshlrev_b32_e32 v21, 16, v17
	v_and_b32_e32 v16, 0xffff0000, v16
	v_and_b32_e32 v17, 0xffff0000, v17
	v_mul_f32_e32 v16, v16, v16
	v_mul_f32_e32 v17, v17, v17
	v_lshlrev_b32_e32 v22, 16, v18
	v_and_b32_e32 v18, 0xffff0000, v18
	v_fmac_f32_e32 v16, v20, v20
	v_fmac_f32_e32 v17, v21, v21
	v_add_f32_e32 v16, v16, v17
	v_mul_f32_e32 v17, v18, v18
	v_lshlrev_b32_e32 v23, 16, v19
	v_and_b32_e32 v19, 0xffff0000, v19
	v_fmac_f32_e32 v17, v22, v22
	v_add_f32_e32 v16, v17, v16
	v_mul_f32_e32 v17, v19, v19
	v_fmac_f32_e32 v17, v23, v23
	v_add_f32_e32 v16, v17, v16
	v_add_f32_e32 v16, v36, v16
	v_mov_b32_e32 v17, v16
	s_nop 1
	v_permlane16_swap_b32_e32 v16, v17
	s_waitcnt lgkmcnt(0)
	v_add_f32_e32 v16, v16, v17
	v_mov_b32_e32 v17, v16
	s_nop 1
	v_permlane32_swap_b32_e32 v16, v17
	s_and_saveexec_b64 s[20:21], s[4:5]
	s_cbranch_execz .LBB0_295
	s_waitcnt lgkmcnt(0)
	v_add_f32_e32 v18, v16, v17
	s_lshl_b32 s22, s34, 2
	v_lshlrev_b64 v[16:17], 6, v[32:33]
	s_ashr_i32 s23, s22, 31
	v_lshl_add_u64 v[16:17], s[14:15], 0, v[16:17]
	v_lshl_add_u64 v[16:17], s[22:23], 2, v[16:17]
	s_lshl_b32 s68, s45, 2
	v_lshl_add_u64 v[16:17], v[16:17], 0, s[68:69]
	global_store_dword v[16:17], v18, off
.LBB0_295:
	s_or_b64 exec, exec, s[20:21]
	v_add_u32_e32 v16, 0xb0, v140
	s_waitcnt lgkmcnt(0)
	v_ashrrev_i32_e32 v17, 31, v16
	v_lshlrev_b64 v[18:19], 11, v[16:17]
	v_lshl_add_u64 v[18:19], s[12:13], 0, v[18:19]
	v_lshl_add_u64 v[18:19], v[138:139], 1, v[18:19]
	s_waitcnt vmcnt(15)
	v_lshlrev_b32_e32 v24, 16, v236
	v_and_b32_e32 v25, 0xffff0000, v236
	v_lshlrev_b32_e32 v20, 16, v237
	v_and_b32_e32 v21, 0xffff0000, v237
	v_lshlrev_b32_e32 v26, 16, v238
	v_and_b32_e32 v27, 0xffff0000, v238
	v_lshlrev_b32_e32 v22, 16, v239
	v_and_b32_e32 v23, 0xffff0000, v239
	v_pk_fma_f32 v[14:15], v[14:15], 0.5, v[20:21] op_sel_hi:[1,0,1]
	v_pk_fma_f32 v[12:13], v[12:13], 0.5, v[24:25] op_sel_hi:[1,0,1]
	v_pk_fma_f32 v[20:21], v[10:11], 0.5, v[22:23] op_sel_hi:[1,0,1]
	v_pk_fma_f32 v[10:11], v[8:9], 0.5, v[26:27] op_sel_hi:[1,0,1]
	v_cvt_pk_bf16_f32 v8, v12, v13
	v_cvt_pk_bf16_f32 v9, v14, v15
	v_cvt_pk_bf16_f32 v10, v10, v11
	v_cvt_pk_bf16_f32 v11, v20, v21
	global_store_dwordx4 v[18:19], v[8:11], off
	v_lshlrev_b32_e32 v12, 16, v8
	v_lshlrev_b32_e32 v13, 16, v9
	v_and_b32_e32 v8, 0xffff0000, v8
	v_and_b32_e32 v9, 0xffff0000, v9
	v_mul_f32_e32 v8, v8, v8
	v_mul_f32_e32 v9, v9, v9
	v_lshlrev_b32_e32 v14, 16, v10
	v_and_b32_e32 v10, 0xffff0000, v10
	v_fmac_f32_e32 v8, v12, v12
	v_fmac_f32_e32 v9, v13, v13
	v_add_f32_e32 v8, v8, v9
	v_mul_f32_e32 v9, v10, v10
	v_lshlrev_b32_e32 v15, 16, v11
	v_and_b32_e32 v11, 0xffff0000, v11
	v_fmac_f32_e32 v9, v14, v14
	v_add_f32_e32 v8, v9, v8
	v_mul_f32_e32 v9, v11, v11
	v_fmac_f32_e32 v9, v15, v15
	v_add_f32_e32 v20, v9, v8
	s_waitcnt vmcnt(15)
	v_lshlrev_b32_e32 v12, 16, v248
	v_and_b32_e32 v13, 0xffff0000, v248
	v_lshlrev_b32_e32 v8, 16, v249
	v_and_b32_e32 v9, 0xffff0000, v249
	v_lshlrev_b32_e32 v14, 16, v250
	v_and_b32_e32 v15, 0xffff0000, v250
	v_lshlrev_b32_e32 v10, 16, v251
	v_and_b32_e32 v11, 0xffff0000, v251
	v_pk_fma_f32 v[6:7], v[6:7], 0.5, v[8:9] op_sel_hi:[1,0,1]
	v_pk_fma_f32 v[4:5], v[4:5], 0.5, v[12:13] op_sel_hi:[1,0,1]
	v_pk_fma_f32 v[8:9], v[2:3], 0.5, v[10:11] op_sel_hi:[1,0,1]
	v_pk_fma_f32 v[2:3], v[0:1], 0.5, v[14:15] op_sel_hi:[1,0,1]
	v_cvt_pk_bf16_f32 v0, v4, v5
	v_cvt_pk_bf16_f32 v1, v6, v7
	v_cvt_pk_bf16_f32 v2, v2, v3
	v_cvt_pk_bf16_f32 v3, v8, v9
	global_store_dwordx4 v[18:19], v[0:3], off offset:256
	v_lshlrev_b32_e32 v4, 16, v0
	v_lshlrev_b32_e32 v5, 16, v1
	v_and_b32_e32 v0, 0xffff0000, v0
	v_and_b32_e32 v1, 0xffff0000, v1
	v_mul_f32_e32 v0, v0, v0
	v_mul_f32_e32 v1, v1, v1
	v_lshlrev_b32_e32 v6, 16, v2
	v_and_b32_e32 v2, 0xffff0000, v2
	v_fmac_f32_e32 v0, v4, v4
	v_fmac_f32_e32 v1, v5, v5
	v_add_f32_e32 v0, v0, v1
	v_mul_f32_e32 v1, v2, v2
	v_lshlrev_b32_e32 v7, 16, v3
	v_and_b32_e32 v3, 0xffff0000, v3
	v_fmac_f32_e32 v1, v6, v6
	v_add_f32_e32 v0, v1, v0
	v_mul_f32_e32 v1, v3, v3
	v_fmac_f32_e32 v1, v7, v7
	v_add_f32_e32 v0, v1, v0
	v_add_f32_e32 v0, v20, v0
	v_mov_b32_e32 v1, v0
	s_nop 1
	v_permlane16_swap_b32_e32 v0, v1
	s_waitcnt lgkmcnt(0)
	v_add_f32_e32 v0, v0, v1
	v_mov_b32_e32 v1, v0
	s_nop 1
	v_permlane32_swap_b32_e32 v0, v1
	s_and_saveexec_b64 s[20:21], s[4:5]
	s_cbranch_execz .LBB0_297
	s_waitcnt lgkmcnt(0)
	v_add_f32_e32 v2, v0, v1
	s_lshl_b32 s22, s34, 2
	v_lshlrev_b64 v[0:1], 6, v[16:17]
	s_ashr_i32 s23, s22, 31
	v_lshl_add_u64 v[0:1], s[14:15], 0, v[0:1]
	v_lshl_add_u64 v[0:1], s[22:23], 2, v[0:1]
	s_lshl_b32 s68, s45, 2
	v_lshl_add_u64 v[0:1], v[0:1], 0, s[68:69]
	global_store_dword v[0:1], v2, off

; __device__ __forceinline__ float bflo(unsigned w) { return __uint_as_float(w << 16); }
; __device__ __forceinline__ float bfhi(unsigned w) { return __uint_as_float(w & 0xffff0000u); }
; __device__ __forceinline__ v4u pack8(const f32x4 a, const f32x4 b) { v4u w; w.x = cvt_pk_bf16(a[0], a[1]); w.y = cvt_pk_bf16(a[2], a[3]); w.z = cvt_pk_bf16(b[0], b[1]); w.w = cvt_pk_bf16(b[2], b[3]); return w; }
;     __device__ __forceinline__ void operator()(const f32x4 (&acc)[2][2][4][2], const pg8::Unit& u, int wr, int wc, int fr, int fq) const {
;         const int row0 = u.pm * 256 + wr * 64 + fr, col0 = u.pn * 256 + wc * 32 + 8 * fq;
; #pragma unroll
;         for (int ai = 0; ai < 2; ++ai)
; #pragma unroll
;             for (int m = 0; m < 4; ++m) {
;                 const int row = row0 + ai * 128 + m * 16; float ss = 0.f;
; #pragma unroll
;                 for (int bj = 0; bj < 2; ++bj) {
;                     const size_t off = (size_t)row * DM + col0 + bj * 128;
;                     const v4u b = *(const v4u*)(xb + off);
;                     f32x4 v0, v1; v0[0] = bflo(b.x); v0[1] = bfhi(b.x); v0[2] = bflo(b.y); v0[3] = bfhi(b.y); v1[0] = bflo(b.z); v1[1] = bfhi(b.z); v1[2] = bflo(b.w); v1[3] = bfhi(b.w);
;                     v0 = v0 + alpha * acc[ai][bj][m][0]; v1 = v1 + alpha * acc[ai][bj][m][1];
;                     const v4u w = pack8(v0, v1); *(v4u*)(xb + off) = w;
;                     const float r0 = bflo(w.x), r1 = bfhi(w.x), r2 = bflo(w.y), r3 = bfhi(w.y), r4 = bflo(w.z), r5 = bfhi(w.z), r6 = bflo(w.w), r7 = bfhi(w.w);
;                     ss += (r0 * r0 + r1 * r1) + (r2 * r2 + r3 * r3) + (r4 * r4 + r5 * r5) + (r6 * r6 + r7 * r7);
;                 }
;                 ss += __shfl_xor(ss, 16); ss += __shfl_xor(ss, 32);
;                 if (fq == 0) ssq[(size_t)row * 16 + u.pn * 4 + wc] = ss;
.LBB0_888:
	v_and_b32_e32 v142, 64, v215
	v_xor_b32_e32 v141, 16, v215
	v_add_u32_e32 v142, 64, v142
	v_cmp_lt_i32_e32 vcc, v141, v142
	v_lshl_add_u32 v140, s26, 8, v144
	v_lshl_or_b32 v138, s8, 8, v146
	v_cndmask_b32_e32 v141, v215, v141, vcc
	v_lshlrev_b32_e32 v148, 2, v141
	v_xor_b32_e32 v141, 32, v215
	v_cmp_lt_i32_e32 vcc, v141, v142
	v_ashrrev_i32_e32 v139, 31, v138
	s_nop 0
	v_cndmask_b32_e32 v141, v215, v141, vcc
	v_lshlrev_b32_e32 v149, 2, v141
	v_ashrrev_i32_e32 v141, 31, v140
	v_lshlrev_b64 v[142:143], 11, v[140:141]
	v_lshl_add_u64 v[142:143], s[12:13], 0, v[142:143]
	v_lshl_add_u64 v[142:143], v[138:139], 1, v[142:143]
	s_waitcnt vmcnt(15)
	v_lshlrev_b32_e32 v154, 16, v160
	v_and_b32_e32 v155, 0xffff0000, v160
	v_lshlrev_b32_e32 v150, 16, v161
	v_and_b32_e32 v151, 0xffff0000, v161
	v_lshlrev_b32_e32 v156, 16, v162
	v_and_b32_e32 v157, 0xffff0000, v162
	v_lshlrev_b32_e32 v152, 16, v163
	v_and_b32_e32 v153, 0xffff0000, v163
	v_pk_add_f32 v[126:127], v[126:127], v[150:151]
	v_pk_add_f32 v[124:125], v[124:125], v[154:155]
	v_pk_add_f32 v[150:151], v[122:123], v[152:153]
	v_pk_add_f32 v[122:123], v[120:121], v[156:157]
	v_cvt_pk_bf16_f32 v120, v124, v125
	v_cvt_pk_bf16_f32 v121, v126, v127
	v_cvt_pk_bf16_f32 v122, v122, v123
	v_cvt_pk_bf16_f32 v123, v150, v151
	global_store_dwordx4 v[142:143], v[120:123], off
	v_lshlrev_b32_e32 v124, 16, v120
	v_lshlrev_b32_e32 v125, 16, v121
	v_and_b32_e32 v120, 0xffff0000, v120
	v_and_b32_e32 v121, 0xffff0000, v121
	v_mul_f32_e32 v120, v120, v120
	v_mul_f32_e32 v121, v121, v121
	v_lshlrev_b32_e32 v126, 16, v122
	v_and_b32_e32 v122, 0xffff0000, v122
	v_fmac_f32_e32 v120, v124, v124
	v_fmac_f32_e32 v121, v125, v125
	v_add_f32_e32 v120, v120, v121
	v_mul_f32_e32 v121, v122, v122
	v_lshlrev_b32_e32 v127, 16, v123
	v_and_b32_e32 v123, 0xffff0000, v123
	v_fmac_f32_e32 v121, v126, v126
	v_add_f32_e32 v120, v121, v120
	v_mul_f32_e32 v121, v123, v123
	v_fmac_f32_e32 v121, v127, v127
	v_add_f32_e32 v150, v121, v120
	s_waitcnt vmcnt(15)
	v_lshlrev_b32_e32 v124, 16, v164
	v_and_b32_e32 v125, 0xffff0000, v164
	v_lshlrev_b32_e32 v120, 16, v165
	v_and_b32_e32 v121, 0xffff0000, v165
	v_lshlrev_b32_e32 v126, 16, v166
	v_and_b32_e32 v127, 0xffff0000, v166
	v_lshlrev_b32_e32 v122, 16, v167
	v_and_b32_e32 v123, 0xffff0000, v167
	v_pk_add_f32 v[118:119], v[118:119], v[120:121]
	v_pk_add_f32 v[116:117], v[116:117], v[124:125]
	v_pk_add_f32 v[120:121], v[114:115], v[122:123]
	v_pk_add_f32 v[114:115], v[112:113], v[126:127]
	v_cvt_pk_bf16_f32 v112, v116, v117
	v_cvt_pk_bf16_f32 v113, v118, v119
	v_cvt_pk_bf16_f32 v114, v114, v115
	v_cvt_pk_bf16_f32 v115, v120, v121
	global_store_dwordx4 v[142:143], v[112:115], off offset:256
	v_lshlrev_b32_e32 v116, 16, v112
	v_lshlrev_b32_e32 v117, 16, v113
	v_and_b32_e32 v112, 0xffff0000, v112
	v_and_b32_e32 v113, 0xffff0000, v113
	v_mul_f32_e32 v112, v112, v112
	v_mul_f32_e32 v113, v113, v113
	v_lshlrev_b32_e32 v118, 16, v114
	v_and_b32_e32 v114, 0xffff0000, v114
	v_fmac_f32_e32 v112, v116, v116
	v_fmac_f32_e32 v113, v117, v117
	v_add_f32_e32 v112, v112, v113
	v_mul_f32_e32 v113, v114, v114
	v_lshlrev_b32_e32 v119, 16, v115
	v_and_b32_e32 v115, 0xffff0000, v115
	v_fmac_f32_e32 v113, v118, v118
	v_add_f32_e32 v112, v113, v112
	v_mul_f32_e32 v113, v115, v115
	v_fmac_f32_e32 v113, v119, v119
	v_add_f32_e32 v112, v113, v112
	v_add_f32_e32 v112, v150, v112
	v_mov_b32_e32 v113, v112
	s_nop 1
	v_permlane16_swap_b32_e32 v112, v113
	s_waitcnt lgkmcnt(0)
	v_add_f32_e32 v112, v112, v113
	v_mov_b32_e32 v113, v112
	s_nop 1
	v_permlane32_swap_b32_e32 v112, v113
	s_and_saveexec_b64 s[26:27], s[4:5]
	s_cbranch_execz .LBB0_890
	s_waitcnt lgkmcnt(0)
	v_add_f32_e32 v114, v112, v113
	s_lshl_b32 s28, s8, 2
	v_lshlrev_b64 v[112:113], 6, v[140:141]
	s_ashr_i32 s29, s28, 31
	v_lshl_add_u64 v[112:113], s[14:15], 0, v[112:113]
	v_lshl_add_u64 v[112:113], s[28:29], 2, v[112:113]
	s_lshl_b32 s68, s51, 2
	v_lshl_add_u64 v[112:113], v[112:113], 0, s[68:69]
	global_store_dword v[112:113], v114, off
.LBB0_890:
	s_or_b64 exec, exec, s[26:27]
	v_or_b32_e32 v112, 16, v140
	s_waitcnt lgkmcnt(0)
	v_ashrrev_i32_e32 v113, 31, v112
	v_lshlrev_b64 v[114:115], 11, v[112:113]
	v_lshl_add_u64 v[114:115], s[12:13], 0, v[114:115]
	v_lshl_add_u64 v[114:115], v[138:139], 1, v[114:115]
	s_waitcnt vmcnt(15)
	v_lshlrev_b32_e32 v120, 16, v168
	v_and_b32_e32 v121, 0xffff0000, v168
	v_lshlrev_b32_e32 v116, 16, v169
	v_and_b32_e32 v117, 0xffff0000, v169
	v_lshlrev_b32_e32 v122, 16, v170
	v_and_b32_e32 v123, 0xffff0000, v170
	v_lshlrev_b32_e32 v118, 16, v171
	v_and_b32_e32 v119, 0xffff0000, v171
	v_pk_add_f32 v[110:111], v[110:111], v[116:117]
	v_pk_add_f32 v[108:109], v[108:109], v[120:121]
	v_pk_add_f32 v[116:117], v[106:107], v[118:119]
	v_pk_add_f32 v[106:107], v[104:105], v[122:123]
	v_cvt_pk_bf16_f32 v104, v108, v109
	v_cvt_pk_bf16_f32 v105, v110, v111
	v_cvt_pk_bf16_f32 v106, v106, v107
	v_cvt_pk_bf16_f32 v107, v116, v117
	global_store_dwordx4 v[114:115], v[104:107], off
	v_lshlrev_b32_e32 v108, 16, v104
	v_lshlrev_b32_e32 v109, 16, v105
	v_and_b32_e32 v104, 0xffff0000, v104
	v_and_b32_e32 v105, 0xffff0000, v105
	v_mul_f32_e32 v104, v104, v104
	v_mul_f32_e32 v105, v105, v105
	v_lshlrev_b32_e32 v110, 16, v106
	v_and_b32_e32 v106, 0xffff0000, v106
	v_fmac_f32_e32 v104, v108, v108
	v_fmac_f32_e32 v105, v109, v109
	v_add_f32_e32 v104, v104, v105
	v_mul_f32_e32 v105, v106, v106
	v_lshlrev_b32_e32 v111, 16, v107
	v_and_b32_e32 v107, 0xffff0000, v107
	v_fmac_f32_e32 v105, v110, v110
	v_add_f32_e32 v104, v105, v104
	v_mul_f32_e32 v105, v107, v107
	v_fmac_f32_e32 v105, v111, v111
	v_add_f32_e32 v116, v105, v104
	s_waitcnt vmcnt(15)
; __device__ __forceinline__ float bflo(unsigned w) { return __uint_as_float(w << 16); }
; __device__ __forceinline__ float bfhi(unsigned w) { return __uint_as_float(w & 0xffff0000u); }
; __device__ __forceinline__ v4u pack8(const f32x4 a, const f32x4 b) { v4u w; w.x = cvt_pk_bf16(a[0], a[1]); w.y = cvt_pk_bf16(a[2], a[3]); w.z = cvt_pk_bf16(b[0], b[1]); w.w = cvt_pk_bf16(b[2], b[3]); return w; }
;     __device__ __forceinline__ void operator()(const f32x4 (&acc)[2][2][4][2], const pg8::Unit& u, int wr, int wc, int fr, int fq) const {
;     ...
;                 const int row = row0 + ai * 128 + m * 16; float ss = 0.f;
; #pragma unroll
;                 for (int bj = 0; bj < 2; ++bj) {
;                     const size_t off = (size_t)row * DM + col0 + bj * 128;
;                     const v4u b = *(const v4u*)(xb + off);
;                     f32x4 v0, v1; v0[0] = bflo(b.x); v0[1] = bfhi(b.x); v0[2] = bflo(b.y); v0[3] = bfhi(b.y); v1[0] = bflo(b.z); v1[1] = bfhi(b.z); v1[2] = bflo(b.w); v1[3] = bfhi(b.w);
;                     v0 = v0 + alpha * acc[ai][bj][m][0]; v1 = v1 + alpha * acc[ai][bj][m][1];
;                     const v4u w = pack8(v0, v1); *(v4u*)(xb + off) = w;
;                     const float r0 = bflo(w.x), r1 = bfhi(w.x), r2 = bflo(w.y), r3 = bfhi(w.y), r4 = bflo(w.z), r5 = bfhi(w.z), r6 = bflo(w.w), r7 = bfhi(w.w);
;                     ss += (r0 * r0 + r1 * r1) + (r2 * r2 + r3 * r3) + (r4 * r4 + r5 * r5) + (r6 * r6 + r7 * r7);
;                 }
;                 ss += __shfl_xor(ss, 16); ss += __shfl_xor(ss, 32);
;                 if (fq == 0) ssq[(size_t)row * 16 + u.pn * 4 + wc] = ss;
	v_lshlrev_b32_e32 v108, 16, v172
	v_and_b32_e32 v109, 0xffff0000, v172
	v_lshlrev_b32_e32 v104, 16, v173
	v_and_b32_e32 v105, 0xffff0000, v173
	v_lshlrev_b32_e32 v110, 16, v174
	v_and_b32_e32 v111, 0xffff0000, v174
	v_lshlrev_b32_e32 v106, 16, v175
	v_and_b32_e32 v107, 0xffff0000, v175
	v_pk_add_f32 v[102:103], v[102:103], v[104:105]
	v_pk_add_f32 v[100:101], v[100:101], v[108:109]
	v_pk_add_f32 v[104:105], v[98:99], v[106:107]
	v_pk_add_f32 v[98:99], v[96:97], v[110:111]
	v_cvt_pk_bf16_f32 v96, v100, v101
	v_cvt_pk_bf16_f32 v97, v102, v103
	v_cvt_pk_bf16_f32 v98, v98, v99
	v_cvt_pk_bf16_f32 v99, v104, v105
	global_store_dwordx4 v[114:115], v[96:99], off offset:256
	v_lshlrev_b32_e32 v100, 16, v96
	v_lshlrev_b32_e32 v101, 16, v97
	v_and_b32_e32 v96, 0xffff0000, v96
	v_and_b32_e32 v97, 0xffff0000, v97
	v_mul_f32_e32 v96, v96, v96
	v_mul_f32_e32 v97, v97, v97
	v_lshlrev_b32_e32 v102, 16, v98
	v_and_b32_e32 v98, 0xffff0000, v98
	v_fmac_f32_e32 v96, v100, v100
	v_fmac_f32_e32 v97, v101, v101
	v_add_f32_e32 v96, v96, v97
	v_mul_f32_e32 v97, v98, v98
	v_lshlrev_b32_e32 v103, 16, v99
	v_and_b32_e32 v99, 0xffff0000, v99
	v_fmac_f32_e32 v97, v102, v102
	v_add_f32_e32 v96, v97, v96
	v_mul_f32_e32 v97, v99, v99
	v_fmac_f32_e32 v97, v103, v103
	v_add_f32_e32 v96, v97, v96
	v_add_f32_e32 v96, v116, v96
	v_mov_b32_e32 v97, v96
	s_nop 1
	v_permlane16_swap_b32_e32 v96, v97
	s_waitcnt lgkmcnt(0)
	v_add_f32_e32 v96, v96, v97
	v_mov_b32_e32 v97, v96
	s_nop 1
	v_permlane32_swap_b32_e32 v96, v97
	s_and_saveexec_b64 s[26:27], s[4:5]
	s_cbranch_execz .LBB0_892
	s_waitcnt lgkmcnt(0)
	v_add_f32_e32 v98, v96, v97
	s_lshl_b32 s28, s8, 2
	v_lshlrev_b64 v[96:97], 6, v[112:113]
	s_ashr_i32 s29, s28, 31
	v_lshl_add_u64 v[96:97], s[14:15], 0, v[96:97]
	v_lshl_add_u64 v[96:97], s[28:29], 2, v[96:97]
	s_lshl_b32 s68, s51, 2
	v_lshl_add_u64 v[96:97], v[96:97], 0, s[68:69]
	global_store_dword v[96:97], v98, off
.LBB0_892:
	s_or_b64 exec, exec, s[26:27]
	v_or_b32_e32 v96, 32, v140
	s_waitcnt lgkmcnt(0)
	v_ashrrev_i32_e32 v97, 31, v96
	v_lshlrev_b64 v[98:99], 11, v[96:97]
	v_lshl_add_u64 v[98:99], s[12:13], 0, v[98:99]
	v_lshl_add_u64 v[98:99], v[138:139], 1, v[98:99]
	s_waitcnt vmcnt(15)
	v_lshlrev_b32_e32 v104, 16, v176
	v_and_b32_e32 v105, 0xffff0000, v176
	v_lshlrev_b32_e32 v100, 16, v177
	v_and_b32_e32 v101, 0xffff0000, v177
	v_lshlrev_b32_e32 v106, 16, v178
	v_and_b32_e32 v107, 0xffff0000, v178
	v_lshlrev_b32_e32 v102, 16, v179
	v_and_b32_e32 v103, 0xffff0000, v179
	v_pk_add_f32 v[94:95], v[94:95], v[100:101]
	v_pk_add_f32 v[92:93], v[92:93], v[104:105]
	v_pk_add_f32 v[100:101], v[90:91], v[102:103]
	v_pk_add_f32 v[90:91], v[88:89], v[106:107]
	v_cvt_pk_bf16_f32 v88, v92, v93
	v_cvt_pk_bf16_f32 v89, v94, v95
	v_cvt_pk_bf16_f32 v90, v90, v91
	v_cvt_pk_bf16_f32 v91, v100, v101
	global_store_dwordx4 v[98:99], v[88:91], off
	v_lshlrev_b32_e32 v92, 16, v88
	v_lshlrev_b32_e32 v93, 16, v89
	v_and_b32_e32 v88, 0xffff0000, v88
	v_and_b32_e32 v89, 0xffff0000, v89
	v_mul_f32_e32 v88, v88, v88
	v_mul_f32_e32 v89, v89, v89
	v_lshlrev_b32_e32 v94, 16, v90
	v_and_b32_e32 v90, 0xffff0000, v90
	v_fmac_f32_e32 v88, v92, v92
	v_fmac_f32_e32 v89, v93, v93
	v_add_f32_e32 v88, v88, v89
	v_mul_f32_e32 v89, v90, v90
	v_lshlrev_b32_e32 v95, 16, v91
	v_and_b32_e32 v91, 0xffff0000, v91
	v_fmac_f32_e32 v89, v94, v94
	v_add_f32_e32 v88, v89, v88
	v_mul_f32_e32 v89, v91, v91
	v_fmac_f32_e32 v89, v95, v95
	v_add_f32_e32 v100, v89, v88
	s_waitcnt vmcnt(15)
	v_lshlrev_b32_e32 v92, 16, v180
	v_and_b32_e32 v93, 0xffff0000, v180
	v_lshlrev_b32_e32 v88, 16, v181
	v_and_b32_e32 v89, 0xffff0000, v181
	v_lshlrev_b32_e32 v94, 16, v182
	v_and_b32_e32 v95, 0xffff0000, v182
	v_lshlrev_b32_e32 v90, 16, v183
	v_and_b32_e32 v91, 0xffff0000, v183
	v_pk_add_f32 v[86:87], v[86:87], v[88:89]
	v_pk_add_f32 v[84:85], v[84:85], v[92:93]
	v_pk_add_f32 v[88:89], v[82:83], v[90:91]
	v_pk_add_f32 v[82:83], v[80:81], v[94:95]
	v_cvt_pk_bf16_f32 v80, v84, v85
	v_cvt_pk_bf16_f32 v81, v86, v87
	v_cvt_pk_bf16_f32 v82, v82, v83
	v_cvt_pk_bf16_f32 v83, v88, v89
	global_store_dwordx4 v[98:99], v[80:83], off offset:256
	v_lshlrev_b32_e32 v84, 16, v80
	v_lshlrev_b32_e32 v85, 16, v81
	v_and_b32_e32 v80, 0xffff0000, v80
	v_and_b32_e32 v81, 0xffff0000, v81
	v_mul_f32_e32 v80, v80, v80
	v_mul_f32_e32 v81, v81, v81
	v_lshlrev_b32_e32 v86, 16, v82
	v_and_b32_e32 v82, 0xffff0000, v82
	v_fmac_f32_e32 v80, v84, v84
	v_fmac_f32_e32 v81, v85, v85
	v_add_f32_e32 v80, v80, v81
	v_mul_f32_e32 v81, v82, v82
	v_lshlrev_b32_e32 v87, 16, v83
	v_and_b32_e32 v83, 0xffff0000, v83
	v_fmac_f32_e32 v81, v86, v86
	v_add_f32_e32 v80, v81, v80
	v_mul_f32_e32 v81, v83, v83
	v_fmac_f32_e32 v81, v87, v87
	v_add_f32_e32 v80, v81, v80
	v_add_f32_e32 v80, v100, v80
	v_mov_b32_e32 v81, v80
	s_nop 1
	v_permlane16_swap_b32_e32 v80, v81
	s_waitcnt lgkmcnt(0)
	v_add_f32_e32 v80, v80, v81
	v_mov_b32_e32 v81, v80
	s_nop 1
	v_permlane32_swap_b32_e32 v80, v81
	s_and_saveexec_b64 s[26:27], s[4:5]
	s_cbranch_execz .LBB0_894
	s_waitcnt lgkmcnt(0)
	v_add_f32_e32 v82, v80, v81
	s_lshl_b32 s28, s8, 2
	v_lshlrev_b64 v[80:81], 6, v[96:97]
	s_ashr_i32 s29, s28, 31
	v_lshl_add_u64 v[80:81], s[14:15], 0, v[80:81]
	v_lshl_add_u64 v[80:81], s[28:29], 2, v[80:81]
	s_lshl_b32 s68, s51, 2
	v_lshl_add_u64 v[80:81], v[80:81], 0, s[68:69]
	global_store_dword v[80:81], v82, off
; __device__ __forceinline__ float bflo(unsigned w) { return __uint_as_float(w << 16); }
; __device__ __forceinline__ float bfhi(unsigned w) { return __uint_as_float(w & 0xffff0000u); }
; __device__ __forceinline__ v4u pack8(const f32x4 a, const f32x4 b) { v4u w; w.x = cvt_pk_bf16(a[0], a[1]); w.y = cvt_pk_bf16(a[2], a[3]); w.z = cvt_pk_bf16(b[0], b[1]); w.w = cvt_pk_bf16(b[2], b[3]); return w; }
;     __device__ __forceinline__ void operator()(const f32x4 (&acc)[2][2][4][2], const pg8::Unit& u, int wr, int wc, int fr, int fq) const {
;     ...
;                 const int row = row0 + ai * 128 + m * 16; float ss = 0.f;
; #pragma unroll
;                 for (int bj = 0; bj < 2; ++bj) {
;                     const size_t off = (size_t)row * DM + col0 + bj * 128;
;                     const v4u b = *(const v4u*)(xb + off);
;                     f32x4 v0, v1; v0[0] = bflo(b.x); v0[1] = bfhi(b.x); v0[2] = bflo(b.y); v0[3] = bfhi(b.y); v1[0] = bflo(b.z); v1[1] = bfhi(b.z); v1[2] = bflo(b.w); v1[3] = bfhi(b.w);
;                     v0 = v0 + alpha * acc[ai][bj][m][0]; v1 = v1 + alpha * acc[ai][bj][m][1];
;                     const v4u w = pack8(v0, v1); *(v4u*)(xb + off) = w;
;                     const float r0 = bflo(w.x), r1 = bfhi(w.x), r2 = bflo(w.y), r3 = bfhi(w.y), r4 = bflo(w.z), r5 = bfhi(w.z), r6 = bflo(w.w), r7 = bfhi(w.w);
;                     ss += (r0 * r0 + r1 * r1) + (r2 * r2 + r3 * r3) + (r4 * r4 + r5 * r5) + (r6 * r6 + r7 * r7);
;                 }
;                 ss += __shfl_xor(ss, 16); ss += __shfl_xor(ss, 32);
;                 if (fq == 0) ssq[(size_t)row * 16 + u.pn * 4 + wc] = ss;
.LBB0_894:
	s_or_b64 exec, exec, s[26:27]
	v_or_b32_e32 v80, 48, v140
	s_waitcnt lgkmcnt(0)
	v_ashrrev_i32_e32 v81, 31, v80
	v_lshlrev_b64 v[82:83], 11, v[80:81]
	v_lshl_add_u64 v[82:83], s[12:13], 0, v[82:83]
	v_lshl_add_u64 v[82:83], v[138:139], 1, v[82:83]
	s_waitcnt vmcnt(15)
	v_lshlrev_b32_e32 v88, 16, v184
	v_and_b32_e32 v89, 0xffff0000, v184
	v_lshlrev_b32_e32 v84, 16, v185
	v_and_b32_e32 v85, 0xffff0000, v185
	v_lshlrev_b32_e32 v90, 16, v186
	v_and_b32_e32 v91, 0xffff0000, v186
	v_lshlrev_b32_e32 v86, 16, v187
	v_and_b32_e32 v87, 0xffff0000, v187
	v_pk_add_f32 v[78:79], v[78:79], v[84:85]
	v_pk_add_f32 v[76:77], v[76:77], v[88:89]
	v_pk_add_f32 v[84:85], v[74:75], v[86:87]
	v_pk_add_f32 v[74:75], v[72:73], v[90:91]
	v_cvt_pk_bf16_f32 v72, v76, v77
	v_cvt_pk_bf16_f32 v73, v78, v79
	v_cvt_pk_bf16_f32 v74, v74, v75
	v_cvt_pk_bf16_f32 v75, v84, v85
	global_store_dwordx4 v[82:83], v[72:75], off
	v_lshlrev_b32_e32 v76, 16, v72
	v_lshlrev_b32_e32 v77, 16, v73
	v_and_b32_e32 v72, 0xffff0000, v72
	v_and_b32_e32 v73, 0xffff0000, v73
	v_mul_f32_e32 v72, v72, v72
	v_mul_f32_e32 v73, v73, v73
	v_lshlrev_b32_e32 v78, 16, v74
	v_and_b32_e32 v74, 0xffff0000, v74
	v_fmac_f32_e32 v72, v76, v76
	v_fmac_f32_e32 v73, v77, v77
	v_add_f32_e32 v72, v72, v73
	v_mul_f32_e32 v73, v74, v74
	v_lshlrev_b32_e32 v79, 16, v75
	v_and_b32_e32 v75, 0xffff0000, v75
	v_fmac_f32_e32 v73, v78, v78
	v_add_f32_e32 v72, v73, v72
	v_mul_f32_e32 v73, v75, v75
	v_fmac_f32_e32 v73, v79, v79
	v_add_f32_e32 v84, v73, v72
	s_waitcnt vmcnt(15)
	v_lshlrev_b32_e32 v76, 16, v188
	v_and_b32_e32 v77, 0xffff0000, v188
	v_lshlrev_b32_e32 v72, 16, v189
	v_and_b32_e32 v73, 0xffff0000, v189
	v_lshlrev_b32_e32 v78, 16, v190
	v_and_b32_e32 v79, 0xffff0000, v190
	v_lshlrev_b32_e32 v74, 16, v191
	v_and_b32_e32 v75, 0xffff0000, v191
	v_pk_add_f32 v[70:71], v[70:71], v[72:73]
	v_pk_add_f32 v[68:69], v[68:69], v[76:77]
	v_pk_add_f32 v[72:73], v[66:67], v[74:75]
	v_pk_add_f32 v[66:67], v[64:65], v[78:79]
	v_cvt_pk_bf16_f32 v64, v68, v69
	v_cvt_pk_bf16_f32 v65, v70, v71
	v_cvt_pk_bf16_f32 v66, v66, v67
	v_cvt_pk_bf16_f32 v67, v72, v73
	global_store_dwordx4 v[82:83], v[64:67], off offset:256
	v_lshlrev_b32_e32 v68, 16, v64
	v_lshlrev_b32_e32 v69, 16, v65
	v_and_b32_e32 v64, 0xffff0000, v64
	v_and_b32_e32 v65, 0xffff0000, v65
	v_mul_f32_e32 v64, v64, v64
	v_mul_f32_e32 v65, v65, v65
	v_lshlrev_b32_e32 v70, 16, v66
	v_and_b32_e32 v66, 0xffff0000, v66
	v_fmac_f32_e32 v64, v68, v68
	v_fmac_f32_e32 v65, v69, v69
	v_add_f32_e32 v64, v64, v65
	v_mul_f32_e32 v65, v66, v66
	v_lshlrev_b32_e32 v71, 16, v67
	v_and_b32_e32 v67, 0xffff0000, v67
	v_fmac_f32_e32 v65, v70, v70
	v_add_f32_e32 v64, v65, v64
	v_mul_f32_e32 v65, v67, v67
	v_fmac_f32_e32 v65, v71, v71
	v_add_f32_e32 v64, v65, v64
	v_add_f32_e32 v64, v84, v64
	v_mov_b32_e32 v65, v64
	s_nop 1
	v_permlane16_swap_b32_e32 v64, v65
	s_waitcnt lgkmcnt(0)
	v_add_f32_e32 v64, v64, v65
	v_mov_b32_e32 v65, v64
	s_nop 1
	v_permlane32_swap_b32_e32 v64, v65
	s_and_saveexec_b64 s[26:27], s[4:5]
	s_cbranch_execz .LBB0_896
	s_waitcnt lgkmcnt(0)
	v_add_f32_e32 v66, v64, v65
	s_lshl_b32 s28, s8, 2
	v_lshlrev_b64 v[64:65], 6, v[80:81]
	s_ashr_i32 s29, s28, 31
	v_lshl_add_u64 v[64:65], s[14:15], 0, v[64:65]
	v_lshl_add_u64 v[64:65], s[28:29], 2, v[64:65]
	s_lshl_b32 s68, s51, 2
	v_lshl_add_u64 v[64:65], v[64:65], 0, s[68:69]
	global_store_dword v[64:65], v66, off
.LBB0_896:
	s_or_b64 exec, exec, s[26:27]
	v_add_u32_e32 v64, 0x80, v140
	s_waitcnt lgkmcnt(0)
	v_ashrrev_i32_e32 v65, 31, v64
	v_lshlrev_b64 v[66:67], 11, v[64:65]
	v_lshl_add_u64 v[66:67], s[12:13], 0, v[66:67]
	v_lshl_add_u64 v[66:67], v[138:139], 1, v[66:67]
	s_waitcnt vmcnt(15)
	v_lshlrev_b32_e32 v72, 16, v204
	v_and_b32_e32 v73, 0xffff0000, v204
	v_lshlrev_b32_e32 v68, 16, v205
	v_and_b32_e32 v69, 0xffff0000, v205
	v_lshlrev_b32_e32 v74, 16, v206
	v_and_b32_e32 v75, 0xffff0000, v206
	v_lshlrev_b32_e32 v70, 16, v207
	v_and_b32_e32 v71, 0xffff0000, v207
	v_pk_add_f32 v[62:63], v[62:63], v[68:69]
	v_pk_add_f32 v[60:61], v[60:61], v[72:73]
	v_pk_add_f32 v[68:69], v[58:59], v[70:71]
	v_pk_add_f32 v[58:59], v[56:57], v[74:75]
	v_cvt_pk_bf16_f32 v56, v60, v61
	v_cvt_pk_bf16_f32 v57, v62, v63
	v_cvt_pk_bf16_f32 v58, v58, v59
	v_cvt_pk_bf16_f32 v59, v68, v69
	global_store_dwordx4 v[66:67], v[56:59], off
	v_lshlrev_b32_e32 v60, 16, v56
	v_lshlrev_b32_e32 v61, 16, v57
	v_and_b32_e32 v56, 0xffff0000, v56
	v_and_b32_e32 v57, 0xffff0000, v57
	v_mul_f32_e32 v56, v56, v56
	v_mul_f32_e32 v57, v57, v57
	v_lshlrev_b32_e32 v62, 16, v58
	v_and_b32_e32 v58, 0xffff0000, v58
	v_fmac_f32_e32 v56, v60, v60
	v_fmac_f32_e32 v57, v61, v61
	v_add_f32_e32 v56, v56, v57
	v_mul_f32_e32 v57, v58, v58
	v_lshlrev_b32_e32 v63, 16, v59
	v_and_b32_e32 v59, 0xffff0000, v59
	v_fmac_f32_e32 v57, v62, v62
	v_add_f32_e32 v56, v57, v56
	v_mul_f32_e32 v57, v59, v59
	v_fmac_f32_e32 v57, v63, v63
	v_add_f32_e32 v68, v57, v56
	s_waitcnt vmcnt(15)
	v_lshlrev_b32_e32 v60, 16, v208
	v_and_b32_e32 v61, 0xffff0000, v208
	v_lshlrev_b32_e32 v56, 16, v209
	v_and_b32_e32 v57, 0xffff0000, v209
	v_lshlrev_b32_e32 v62, 16, v210
	v_and_b32_e32 v63, 0xffff0000, v210
	v_lshlrev_b32_e32 v58, 16, v211
	v_and_b32_e32 v59, 0xffff0000, v211
	v_pk_add_f32 v[54:55], v[54:55], v[56:57]
	v_pk_add_f32 v[52:53], v[52:53], v[60:61]
	v_pk_add_f32 v[56:57], v[50:51], v[58:59]
	v_pk_add_f32 v[50:51], v[48:49], v[62:63]
	v_cvt_pk_bf16_f32 v48, v52, v53
	v_cvt_pk_bf16_f32 v49, v54, v55
	v_cvt_pk_bf16_f32 v50, v50, v51
	v_cvt_pk_bf16_f32 v51, v56, v57
	global_store_dwordx4 v[66:67], v[48:51], off offset:256
	v_lshlrev_b32_e32 v52, 16, v48
	v_lshlrev_b32_e32 v53, 16, v49
	v_and_b32_e32 v48, 0xffff0000, v48
	v_and_b32_e32 v49, 0xffff0000, v49
	v_mul_f32_e32 v48, v48, v48
	v_mul_f32_e32 v49, v49, v49
	v_lshlrev_b32_e32 v54, 16, v50
	v_and_b32_e32 v50, 0xffff0000, v50
	v_fmac_f32_e32 v48, v52, v52
	v_fmac_f32_e32 v49, v53, v53
	v_add_f32_e32 v48, v48, v49
	v_mul_f32_e32 v49, v50, v50
	v_lshlrev_b32_e32 v55, 16, v51
	v_and_b32_e32 v51, 0xffff0000, v51
	v_fmac_f32_e32 v49, v54, v54
	v_add_f32_e32 v48, v49, v48
	v_mul_f32_e32 v49, v51, v51
	v_fmac_f32_e32 v49, v55, v55
	v_add_f32_e32 v48, v49, v48
	v_add_f32_e32 v48, v68, v48
	v_mov_b32_e32 v49, v48
	s_nop 1
	v_permlane16_swap_b32_e32 v48, v49
	s_waitcnt lgkmcnt(0)
	v_add_f32_e32 v48, v48, v49
	v_mov_b32_e32 v49, v48
	s_nop 1
	v_permlane32_swap_b32_e32 v48, v49
	s_and_saveexec_b64 s[26:27], s[4:5]
	s_cbranch_execz .LBB0_898
	s_waitcnt lgkmcnt(0)
	v_add_f32_e32 v50, v48, v49
	s_lshl_b32 s28, s8, 2
	v_lshlrev_b64 v[48:49], 6, v[64:65]
	s_ashr_i32 s29, s28, 31
	v_lshl_add_u64 v[48:49], s[14:15], 0, v[48:49]
	v_lshl_add_u64 v[48:49], s[28:29], 2, v[48:49]
	s_lshl_b32 s68, s51, 2
	v_lshl_add_u64 v[48:49], v[48:49], 0, s[68:69]
	global_store_dword v[48:49], v50, off
; __device__ __forceinline__ float bflo(unsigned w) { return __uint_as_float(w << 16); }
; __device__ __forceinline__ float bfhi(unsigned w) { return __uint_as_float(w & 0xffff0000u); }
; __device__ __forceinline__ v4u pack8(const f32x4 a, const f32x4 b) { v4u w; w.x = cvt_pk_bf16(a[0], a[1]); w.y = cvt_pk_bf16(a[2], a[3]); w.z = cvt_pk_bf16(b[0], b[1]); w.w = cvt_pk_bf16(b[2], b[3]); return w; }
;     __device__ __forceinline__ void operator()(const f32x4 (&acc)[2][2][4][2], const pg8::Unit& u, int wr, int wc, int fr, int fq) const {
;     ...
;                 const int row = row0 + ai * 128 + m * 16; float ss = 0.f;
; #pragma unroll
;                 for (int bj = 0; bj < 2; ++bj) {
;                     const size_t off = (size_t)row * DM + col0 + bj * 128;
;                     const v4u b = *(const v4u*)(xb + off);
;                     f32x4 v0, v1; v0[0] = bflo(b.x); v0[1] = bfhi(b.x); v0[2] = bflo(b.y); v0[3] = bfhi(b.y); v1[0] = bflo(b.z); v1[1] = bfhi(b.z); v1[2] = bflo(b.w); v1[3] = bfhi(b.w);
;                     v0 = v0 + alpha * acc[ai][bj][m][0]; v1 = v1 + alpha * acc[ai][bj][m][1];
;                     const v4u w = pack8(v0, v1); *(v4u*)(xb + off) = w;
;                     const float r0 = bflo(w.x), r1 = bfhi(w.x), r2 = bflo(w.y), r3 = bfhi(w.y), r4 = bflo(w.z), r5 = bfhi(w.z), r6 = bflo(w.w), r7 = bfhi(w.w);
;                     ss += (r0 * r0 + r1 * r1) + (r2 * r2 + r3 * r3) + (r4 * r4 + r5 * r5) + (r6 * r6 + r7 * r7);
;                 }
;                 ss += __shfl_xor(ss, 16); ss += __shfl_xor(ss, 32);
;                 if (fq == 0) ssq[(size_t)row * 16 + u.pn * 4 + wc] = ss;
.LBB0_898:
	s_or_b64 exec, exec, s[26:27]
	v_add_u32_e32 v48, 0x90, v140
	s_waitcnt lgkmcnt(0)
	v_ashrrev_i32_e32 v49, 31, v48
	v_lshlrev_b64 v[50:51], 11, v[48:49]
	v_lshl_add_u64 v[50:51], s[12:13], 0, v[50:51]
	v_lshl_add_u64 v[50:51], v[138:139], 1, v[50:51]
	s_waitcnt vmcnt(15)
	v_lshlrev_b32_e32 v56, 16, v220
	v_and_b32_e32 v57, 0xffff0000, v220
	v_lshlrev_b32_e32 v52, 16, v221
	v_and_b32_e32 v53, 0xffff0000, v221
	v_lshlrev_b32_e32 v58, 16, v222
	v_and_b32_e32 v59, 0xffff0000, v222
	v_lshlrev_b32_e32 v54, 16, v223
	v_and_b32_e32 v55, 0xffff0000, v223
	v_pk_add_f32 v[46:47], v[46:47], v[52:53]
	v_pk_add_f32 v[44:45], v[44:45], v[56:57]
	v_pk_add_f32 v[52:53], v[42:43], v[54:55]
	v_pk_add_f32 v[42:43], v[40:41], v[58:59]
	v_cvt_pk_bf16_f32 v40, v44, v45
	v_cvt_pk_bf16_f32 v41, v46, v47
	v_cvt_pk_bf16_f32 v42, v42, v43
	v_cvt_pk_bf16_f32 v43, v52, v53
	global_store_dwordx4 v[50:51], v[40:43], off
	v_lshlrev_b32_e32 v44, 16, v40
	v_lshlrev_b32_e32 v45, 16, v41
	v_and_b32_e32 v40, 0xffff0000, v40
	v_and_b32_e32 v41, 0xffff0000, v41
	v_mul_f32_e32 v40, v40, v40
	v_mul_f32_e32 v41, v41, v41
	v_lshlrev_b32_e32 v46, 16, v42
	v_and_b32_e32 v42, 0xffff0000, v42
	v_fmac_f32_e32 v40, v44, v44
	v_fmac_f32_e32 v41, v45, v45
	v_add_f32_e32 v40, v40, v41
	v_mul_f32_e32 v41, v42, v42
	v_lshlrev_b32_e32 v47, 16, v43
	v_and_b32_e32 v43, 0xffff0000, v43
	v_fmac_f32_e32 v41, v46, v46
	v_add_f32_e32 v40, v41, v40
	v_mul_f32_e32 v41, v43, v43
	v_fmac_f32_e32 v41, v47, v47
	v_add_f32_e32 v52, v41, v40
	s_waitcnt vmcnt(15)
	v_lshlrev_b32_e32 v44, 16, v224
	v_and_b32_e32 v45, 0xffff0000, v224
	v_lshlrev_b32_e32 v40, 16, v225
	v_and_b32_e32 v41, 0xffff0000, v225
	v_lshlrev_b32_e32 v46, 16, v226
	v_and_b32_e32 v47, 0xffff0000, v226
	v_lshlrev_b32_e32 v42, 16, v227
	v_and_b32_e32 v43, 0xffff0000, v227
	v_pk_add_f32 v[38:39], v[38:39], v[40:41]
	v_pk_add_f32 v[36:37], v[36:37], v[44:45]
	v_pk_add_f32 v[40:41], v[34:35], v[42:43]
	v_pk_add_f32 v[34:35], v[32:33], v[46:47]
	v_cvt_pk_bf16_f32 v32, v36, v37
	v_cvt_pk_bf16_f32 v33, v38, v39
	v_cvt_pk_bf16_f32 v34, v34, v35
	v_cvt_pk_bf16_f32 v35, v40, v41
	global_store_dwordx4 v[50:51], v[32:35], off offset:256
	v_lshlrev_b32_e32 v36, 16, v32
	v_lshlrev_b32_e32 v37, 16, v33
	v_and_b32_e32 v32, 0xffff0000, v32
	v_and_b32_e32 v33, 0xffff0000, v33
	v_mul_f32_e32 v32, v32, v32
	v_mul_f32_e32 v33, v33, v33
	v_lshlrev_b32_e32 v38, 16, v34
	v_and_b32_e32 v34, 0xffff0000, v34
	v_fmac_f32_e32 v32, v36, v36
	v_fmac_f32_e32 v33, v37, v37
	v_add_f32_e32 v32, v32, v33
	v_mul_f32_e32 v33, v34, v34
	v_lshlrev_b32_e32 v39, 16, v35
	v_and_b32_e32 v35, 0xffff0000, v35
	v_fmac_f32_e32 v33, v38, v38
	v_add_f32_e32 v32, v33, v32
	v_mul_f32_e32 v33, v35, v35
	v_fmac_f32_e32 v33, v39, v39
	v_add_f32_e32 v32, v33, v32
	v_add_f32_e32 v32, v52, v32
	v_mov_b32_e32 v33, v32
	s_nop 1
	v_permlane16_swap_b32_e32 v32, v33
	s_waitcnt lgkmcnt(0)
	v_add_f32_e32 v32, v32, v33
	v_mov_b32_e32 v33, v32
	s_nop 1
	v_permlane32_swap_b32_e32 v32, v33
	s_and_saveexec_b64 s[26:27], s[4:5]
	s_cbranch_execz .LBB0_900
	s_waitcnt lgkmcnt(0)
	v_add_f32_e32 v34, v32, v33
	s_lshl_b32 s28, s8, 2
	v_lshlrev_b64 v[32:33], 6, v[48:49]
	s_ashr_i32 s29, s28, 31
	v_lshl_add_u64 v[32:33], s[14:15], 0, v[32:33]
	v_lshl_add_u64 v[32:33], s[28:29], 2, v[32:33]
	s_lshl_b32 s68, s51, 2
	v_lshl_add_u64 v[32:33], v[32:33], 0, s[68:69]
	global_store_dword v[32:33], v34, off
; __device__ __forceinline__ float bflo(unsigned w) { return __uint_as_float(w << 16); }
; __device__ __forceinline__ float bfhi(unsigned w) { return __uint_as_float(w & 0xffff0000u); }
; __device__ __forceinline__ v4u pack8(const f32x4 a, const f32x4 b) { v4u w; w.x = cvt_pk_bf16(a[0], a[1]); w.y = cvt_pk_bf16(a[2], a[3]); w.z = cvt_pk_bf16(b[0], b[1]); w.w = cvt_pk_bf16(b[2], b[3]); return w; }
;     __device__ __forceinline__ void operator()(const f32x4 (&acc)[2][2][4][2], const pg8::Unit& u, int wr, int wc, int fr, int fq) const {
;         const int row0 = u.pm * 256 + wr * 64 + fr, col0 = u.pn * 256 + wc * 32 + 8 * fq;
; #pragma unroll
;         for (int ai = 0; ai < 2; ++ai)
; #pragma unroll
;             for (int m = 0; m < 4; ++m) {
;                 const int row = row0 + ai * 128 + m * 16; float ss = 0.f;
; #pragma unroll
;                 for (int bj = 0; bj < 2; ++bj) {
;                     const size_t off = (size_t)row * DM + col0 + bj * 128;
;                     const v4u b = *(const v4u*)(xb + off);
;                     f32x4 v0, v1; v0[0] = bflo(b.x); v0[1] = bfhi(b.x); v0[2] = bflo(b.y); v0[3] = bfhi(b.y); v1[0] = bflo(b.z); v1[1] = bfhi(b.z); v1[2] = bflo(b.w); v1[3] = bfhi(b.w);
;                     v0 = v0 + alpha * acc[ai][bj][m][0]; v1 = v1 + alpha * acc[ai][bj][m][1];
;                     const v4u w = pack8(v0, v1); *(v4u*)(xb + off) = w;
;                     const float r0 = bflo(w.x), r1 = bfhi(w.x), r2 = bflo(w.y), r3 = bfhi(w.y), r4 = bflo(w.z), r5 = bfhi(w.z), r6 = bflo(w.w), r7 = bfhi(w.w);
;                     ss += (r0 * r0 + r1 * r1) + (r2 * r2 + r3 * r3) + (r4 * r4 + r5 * r5) + (r6 * r6 + r7 * r7);
;                 }
;                 ss += __shfl_xor(ss, 16); ss += __shfl_xor(ss, 32);
;                 if (fq == 0) ssq[(size_t)row * 16 + u.pn * 4 + wc] = ss;
;             }
.LBB0_900:
	s_or_b64 exec, exec, s[26:27]
	v_add_u32_e32 v32, 0xa0, v140
	s_waitcnt lgkmcnt(0)
	v_ashrrev_i32_e32 v33, 31, v32
	v_lshlrev_b64 v[34:35], 11, v[32:33]
	v_lshl_add_u64 v[34:35], s[12:13], 0, v[34:35]
	v_lshl_add_u64 v[34:35], v[138:139], 1, v[34:35]
	s_waitcnt vmcnt(15)
	v_lshlrev_b32_e32 v40, 16, v228
	v_and_b32_e32 v41, 0xffff0000, v228
	v_lshlrev_b32_e32 v36, 16, v229
	v_and_b32_e32 v37, 0xffff0000, v229
	v_lshlrev_b32_e32 v42, 16, v230
	v_and_b32_e32 v43, 0xffff0000, v230
	v_lshlrev_b32_e32 v38, 16, v231
	v_and_b32_e32 v39, 0xffff0000, v231
	v_pk_add_f32 v[30:31], v[30:31], v[36:37]
	v_pk_add_f32 v[28:29], v[28:29], v[40:41]
	v_pk_add_f32 v[36:37], v[26:27], v[38:39]
	v_pk_add_f32 v[26:27], v[24:25], v[42:43]
	v_cvt_pk_bf16_f32 v24, v28, v29
	v_cvt_pk_bf16_f32 v25, v30, v31
	v_cvt_pk_bf16_f32 v26, v26, v27
	v_cvt_pk_bf16_f32 v27, v36, v37
	global_store_dwordx4 v[34:35], v[24:27], off
	v_lshlrev_b32_e32 v28, 16, v24
	v_lshlrev_b32_e32 v29, 16, v25
	v_and_b32_e32 v24, 0xffff0000, v24
	v_and_b32_e32 v25, 0xffff0000, v25
	v_mul_f32_e32 v24, v24, v24
	v_mul_f32_e32 v25, v25, v25
	v_lshlrev_b32_e32 v30, 16, v26
	v_and_b32_e32 v26, 0xffff0000, v26
	v_fmac_f32_e32 v24, v28, v28
	v_fmac_f32_e32 v25, v29, v29
	v_add_f32_e32 v24, v24, v25
	v_mul_f32_e32 v25, v26, v26
	v_lshlrev_b32_e32 v31, 16, v27
	v_and_b32_e32 v27, 0xffff0000, v27
	v_fmac_f32_e32 v25, v30, v30
	v_add_f32_e32 v24, v25, v24
	v_mul_f32_e32 v25, v27, v27
	v_fmac_f32_e32 v25, v31, v31
	v_add_f32_e32 v36, v25, v24
	s_waitcnt vmcnt(15)
	v_lshlrev_b32_e32 v28, 16, v232
	v_and_b32_e32 v29, 0xffff0000, v232
	v_lshlrev_b32_e32 v24, 16, v233
	v_and_b32_e32 v25, 0xffff0000, v233
	v_lshlrev_b32_e32 v30, 16, v234
	v_and_b32_e32 v31, 0xffff0000, v234
	v_lshlrev_b32_e32 v26, 16, v235
	v_and_b32_e32 v27, 0xffff0000, v235
	v_pk_add_f32 v[22:23], v[22:23], v[24:25]
	v_pk_add_f32 v[20:21], v[20:21], v[28:29]
	v_pk_add_f32 v[24:25], v[18:19], v[26:27]
	v_pk_add_f32 v[18:19], v[16:17], v[30:31]
	v_cvt_pk_bf16_f32 v16, v20, v21
	v_cvt_pk_bf16_f32 v17, v22, v23
	v_cvt_pk_bf16_f32 v18, v18, v19
	v_cvt_pk_bf16_f32 v19, v24, v25
	global_store_dwordx4 v[34:35], v[16:19], off offset:256
	v_lshlrev_b32_e32 v20, 16, v16
	v_lshlrev_b32_e32 v21, 16, v17
	v_and_b32_e32 v16, 0xffff0000, v16
	v_and_b32_e32 v17, 0xffff0000, v17
	v_mul_f32_e32 v16, v16, v16
	v_mul_f32_e32 v17, v17, v17
	v_lshlrev_b32_e32 v22, 16, v18
	v_and_b32_e32 v18, 0xffff0000, v18
	v_fmac_f32_e32 v16, v20, v20
	v_fmac_f32_e32 v17, v21, v21
	v_add_f32_e32 v16, v16, v17
	v_mul_f32_e32 v17, v18, v18
	v_lshlrev_b32_e32 v23, 16, v19
	v_and_b32_e32 v19, 0xffff0000, v19
	v_fmac_f32_e32 v17, v22, v22
	v_add_f32_e32 v16, v17, v16
	v_mul_f32_e32 v17, v19, v19
	v_fmac_f32_e32 v17, v23, v23
	v_add_f32_e32 v16, v17, v16
	v_add_f32_e32 v16, v36, v16
	v_mov_b32_e32 v17, v16
	s_nop 1
	v_permlane16_swap_b32_e32 v16, v17
	s_waitcnt lgkmcnt(0)
	v_add_f32_e32 v16, v16, v17
	v_mov_b32_e32 v17, v16
	s_nop 1
	v_permlane32_swap_b32_e32 v16, v17
	s_and_saveexec_b64 s[26:27], s[4:5]
	s_cbranch_execz .LBB0_902
	s_waitcnt lgkmcnt(0)
	v_add_f32_e32 v18, v16, v17
	s_lshl_b32 s28, s8, 2
	v_lshlrev_b64 v[16:17], 6, v[32:33]
	s_ashr_i32 s29, s28, 31
	v_lshl_add_u64 v[16:17], s[14:15], 0, v[16:17]
	v_lshl_add_u64 v[16:17], s[28:29], 2, v[16:17]
	s_lshl_b32 s68, s51, 2
	v_lshl_add_u64 v[16:17], v[16:17], 0, s[68:69]
	global_store_dword v[16:17], v18, off
.LBB0_902:
	s_or_b64 exec, exec, s[26:27]
	v_add_u32_e32 v16, 0xb0, v140
	s_waitcnt lgkmcnt(0)
	v_ashrrev_i32_e32 v17, 31, v16
	v_lshlrev_b64 v[18:19], 11, v[16:17]
	v_lshl_add_u64 v[18:19], s[12:13], 0, v[18:19]
	v_lshl_add_u64 v[18:19], v[138:139], 1, v[18:19]
	s_waitcnt vmcnt(15)
	v_lshlrev_b32_e32 v24, 16, v236
	v_and_b32_e32 v25, 0xffff0000, v236
	v_lshlrev_b32_e32 v20, 16, v237
	v_and_b32_e32 v21, 0xffff0000, v237
	v_lshlrev_b32_e32 v26, 16, v238
	v_and_b32_e32 v27, 0xffff0000, v238
	v_lshlrev_b32_e32 v22, 16, v239
	v_and_b32_e32 v23, 0xffff0000, v239
	v_pk_add_f32 v[14:15], v[14:15], v[20:21]
	v_pk_add_f32 v[12:13], v[12:13], v[24:25]
	v_pk_add_f32 v[20:21], v[10:11], v[22:23]
	v_pk_add_f32 v[10:11], v[8:9], v[26:27]
	v_cvt_pk_bf16_f32 v8, v12, v13
	v_cvt_pk_bf16_f32 v9, v14, v15
	v_cvt_pk_bf16_f32 v10, v10, v11
	v_cvt_pk_bf16_f32 v11, v20, v21
	global_store_dwordx4 v[18:19], v[8:11], off
	v_lshlrev_b32_e32 v12, 16, v8
	v_lshlrev_b32_e32 v13, 16, v9
	v_and_b32_e32 v8, 0xffff0000, v8
	v_and_b32_e32 v9, 0xffff0000, v9
	v_mul_f32_e32 v8, v8, v8
	v_mul_f32_e32 v9, v9, v9
	v_lshlrev_b32_e32 v14, 16, v10
	v_and_b32_e32 v10, 0xffff0000, v10
	v_fmac_f32_e32 v8, v12, v12
	v_fmac_f32_e32 v9, v13, v13
	v_add_f32_e32 v8, v8, v9
	v_mul_f32_e32 v9, v10, v10
	v_lshlrev_b32_e32 v15, 16, v11
	v_and_b32_e32 v11, 0xffff0000, v11
	v_fmac_f32_e32 v9, v14, v14
	v_add_f32_e32 v8, v9, v8
	v_mul_f32_e32 v9, v11, v11
	v_fmac_f32_e32 v9, v15, v15
	v_add_f32_e32 v20, v9, v8
	s_waitcnt vmcnt(15)
	v_lshlrev_b32_e32 v12, 16, v248
	v_and_b32_e32 v13, 0xffff0000, v248
	v_lshlrev_b32_e32 v8, 16, v249
	v_and_b32_e32 v9, 0xffff0000, v249
	v_lshlrev_b32_e32 v14, 16, v250
	v_and_b32_e32 v15, 0xffff0000, v250
	v_lshlrev_b32_e32 v10, 16, v251
	v_and_b32_e32 v11, 0xffff0000, v251
	v_pk_add_f32 v[6:7], v[6:7], v[8:9]
	v_pk_add_f32 v[4:5], v[4:5], v[12:13]
	v_pk_add_f32 v[8:9], v[2:3], v[10:11]
	v_pk_add_f32 v[2:3], v[0:1], v[14:15]
	v_cvt_pk_bf16_f32 v0, v4, v5
	v_cvt_pk_bf16_f32 v1, v6, v7
	v_cvt_pk_bf16_f32 v2, v2, v3
	v_cvt_pk_bf16_f32 v3, v8, v9
	global_store_dwordx4 v[18:19], v[0:3], off offset:256
	v_lshlrev_b32_e32 v4, 16, v0
	v_lshlrev_b32_e32 v5, 16, v1
	v_and_b32_e32 v0, 0xffff0000, v0
	v_and_b32_e32 v1, 0xffff0000, v1
	v_mul_f32_e32 v0, v0, v0
	v_mul_f32_e32 v1, v1, v1
	v_lshlrev_b32_e32 v6, 16, v2
	v_and_b32_e32 v2, 0xffff0000, v2
	v_fmac_f32_e32 v0, v4, v4
	v_fmac_f32_e32 v1, v5, v5
	v_add_f32_e32 v0, v0, v1
	v_mul_f32_e32 v1, v2, v2
	v_lshlrev_b32_e32 v7, 16, v3
	v_and_b32_e32 v3, 0xffff0000, v3
	v_fmac_f32_e32 v1, v6, v6
	v_add_f32_e32 v0, v1, v0
	v_mul_f32_e32 v1, v3, v3
	v_fmac_f32_e32 v1, v7, v7
	v_add_f32_e32 v0, v1, v0
	v_add_f32_e32 v0, v20, v0
	v_mov_b32_e32 v1, v0
	s_nop 1
	v_permlane16_swap_b32_e32 v0, v1
	s_waitcnt lgkmcnt(0)
	v_add_f32_e32 v0, v0, v1
	v_mov_b32_e32 v1, v0
	s_nop 1
	v_permlane32_swap_b32_e32 v0, v1
	s_and_saveexec_b64 s[26:27], s[4:5]
	s_cbranch_execz .LBB0_904
	s_waitcnt lgkmcnt(0)
	v_add_f32_e32 v2, v0, v1
	s_lshl_b32 s28, s8, 2
	v_lshlrev_b64 v[0:1], 6, v[16:17]
	s_ashr_i32 s29, s28, 31
	v_lshl_add_u64 v[0:1], s[14:15], 0, v[0:1]
	v_lshl_add_u64 v[0:1], s[28:29], 2, v[0:1]
	s_lshl_b32 s68, s51, 2
	v_lshl_add_u64 v[0:1], v[0:1], 0, s[68:69]
	global_store_dword v[0:1], v2, off

; __device__ __forceinline__ float row_rstd(const float* ssq, int row, int fq) {
;     const f32x4 v = *(const f32x4*)(ssq + (size_t)row * 16 + fq * 4);
;     float s = (v[0] + v[1]) + (v[2] + v[3]);
;     s += __shfl_xor(s, 16); s += __shfl_xor(s, 32);
;     return __builtin_amdgcn_rsqf(s * (1.f / DM) + EPS);
; }
;     __device__ __forceinline__ void operator()(const f32x4 (&acc_)[2][2][4][2], const pg8::Unit& u, int wr, int wc, int fr, int fq) const {
;     ...
;         const int row0 = u.pm * 256 + wr * 64 + fr, lrow0 = wr * 64 + fr;
; #pragma unroll
;         for (int ai = 0; ai < 2; ++ai)
; #pragma unroll
;             for (int m = 0; m < 4; ++m) { const float rs = row_rstd(ssq, row0 + ai * 128 + m * 16, fq); float mx = -3.0e38f;
; #pragma unroll
;                 for (int bj = 0; bj < 2; ++bj)
; #pragma unroll
;                     for (int n = 0; n < 2; ++n) { const f32x4 a = acc[ai][bj][m][n]; mx = fmaxf(mx, fmaxf(fmaxf(a[0], a[1]), fmaxf(a[2], a[3]))); }
;                 mx *= rs; mx = fmaxf(mx, __shfl_xor(mx, 16)); mx = fmaxf(mx, __shfl_xor(mx, 32));
;                 if (fq == 0) xch[(lrow0 + ai * 128 + m * 16) * 4 + wc] = mx; }
.LBB0_998:
	s_waitcnt vmcnt(0)
	v_add_f32_e32 v144, v144, v145
	v_add_f32_e32 v146, v146, v147
	v_add_f32_e32 v148, v148, v149
	v_add_f32_e32 v150, v150, v151
	v_add_f32_e32 v152, v152, v153
	v_add_f32_e32 v154, v154, v155
	v_add_f32_e32 v156, v156, v157
	v_add_f32_e32 v158, v158, v159
	v_add_f32_e32 v160, v160, v161
	v_add_f32_e32 v162, v162, v163
	v_add_f32_e32 v164, v164, v165
	v_add_f32_e32 v166, v166, v167
	v_add_f32_e32 v168, v168, v169
	v_add_f32_e32 v170, v170, v171
	v_add_f32_e32 v222, v222, v223
	v_add_f32_e32 v224, v224, v225
	v_add_f32_e32 v144, v144, v146
	v_add_f32_e32 v148, v148, v150
	v_add_f32_e32 v152, v152, v154
	v_add_f32_e32 v156, v156, v158
	v_add_f32_e32 v160, v160, v162
	v_add_f32_e32 v164, v164, v166
	v_add_f32_e32 v168, v168, v170
	v_add_f32_e32 v222, v222, v224
	ds_bpermute_b32 v145, v226, v144
	ds_bpermute_b32 v149, v226, v148
	ds_bpermute_b32 v153, v226, v152
	ds_bpermute_b32 v157, v226, v156
	ds_bpermute_b32 v161, v226, v160
	ds_bpermute_b32 v165, v226, v164
	ds_bpermute_b32 v169, v226, v168
	ds_bpermute_b32 v223, v226, v222
	s_waitcnt lgkmcnt(0)
	v_add_f32_e32 v144, v144, v145
	v_add_f32_e32 v148, v148, v149
	v_add_f32_e32 v152, v152, v153
	v_add_f32_e32 v156, v156, v157
	v_add_f32_e32 v160, v160, v161
	v_add_f32_e32 v164, v164, v165
	v_add_f32_e32 v168, v168, v169
	v_add_f32_e32 v222, v222, v223
	ds_bpermute_b32 v145, v227, v144
	ds_bpermute_b32 v149, v227, v148
	ds_bpermute_b32 v153, v227, v152
	ds_bpermute_b32 v157, v227, v156
	ds_bpermute_b32 v161, v227, v160
	ds_bpermute_b32 v165, v227, v164
	ds_bpermute_b32 v169, v227, v168
	ds_bpermute_b32 v223, v227, v222
	s_waitcnt lgkmcnt(0)
	v_add_f32_e32 v144, v144, v145
	v_add_f32_e32 v148, v148, v149
	v_add_f32_e32 v152, v152, v153
	v_add_f32_e32 v156, v156, v157
	v_add_f32_e32 v160, v160, v161
	v_add_f32_e32 v164, v164, v165
	v_add_f32_e32 v168, v168, v169
	v_add_f32_e32 v222, v222, v223
	v_fmamk_f32 v144, v144, 0x3a800000, v212
	v_fmamk_f32 v148, v148, 0x3a800000, v212
	v_fmamk_f32 v152, v152, 0x3a800000, v212
	v_fmamk_f32 v156, v156, 0x3a800000, v212
	v_fmamk_f32 v160, v160, 0x3a800000, v212
	v_fmamk_f32 v164, v164, 0x3a800000, v212
	v_fmamk_f32 v168, v168, 0x3a800000, v212
	v_fmamk_f32 v222, v222, 0x3a800000, v212
	v_rsq_f32_e32 v246, v144
	v_rsq_f32_e32 v247, v148
	v_rsq_f32_e32 v248, v152
	v_rsq_f32_e32 v249, v156
	v_rsq_f32_e32 v250, v160
	v_rsq_f32_e32 v251, v164
	v_rsq_f32_e32 v252, v168
	v_rsq_f32_e32 v253, v222
	s_nop 0
	v_and_b32_e32 v144, 64, v215
	v_xor_b32_e32 v143, 16, v215
	v_add_u32_e32 v144, 64, v144
	v_cmp_lt_i32_e32 vcc, v143, v144
	v_lshl_add_u32 v142, s24, 8, v174
	s_mov_b32 s2, 0xff61b1e6
	v_cndmask_b32_e32 v143, v215, v143, vcc
	v_lshlrev_b32_e32 v209, 2, v143
	v_xor_b32_e32 v143, 32, v215
	v_cmp_lt_i32_e32 vcc, v143, v144
	v_max_f32_e32 v148, v114, v114
	v_add_u32_e32 v210, s74, v176
	v_cndmask_b32_e32 v143, v215, v143, vcc
	v_lshlrev_b32_e32 v208, 2, v143
	v_ashrrev_i32_e32 v143, 31, v142
	v_lshlrev_b64 v[144:145], 6, v[142:143]
	v_lshl_add_u64 v[158:159], v[136:137], 0, v[144:145]
	s_nop 0
	s_waitcnt lgkmcnt(0)
	s_nop 3
	v_max_f32_e32 v146, v126, v126
	v_max_f32_e32 v147, v122, v122
	s_waitcnt lgkmcnt(0)
	s_nop 1
	s_waitcnt lgkmcnt(0)
	s_nop 0
	v_max_f32_e32 v145, v127, v127
	v_max_f32_e32 v145, v146, v145
	v_max_f32_e32 v146, v123, v123
	v_max_f32_e32 v146, v147, v146
	v_max3_f32 v145, v124, v125, v145
	v_max3_f32 v146, v120, v121, v146
	s_nop 0
	v_max3_f32 v145, v145, s2, v146
	v_max_f32_e32 v146, v119, v119
	v_max_f32_e32 v147, v118, v118
	v_max_f32_e32 v146, v147, v146
	v_max_f32_e32 v147, v115, v115
	v_mov_b32_e32 v144, v246
	v_max_f32_e32 v147, v148, v147
	v_max3_f32 v146, v116, v117, v146
	v_max3_f32 v147, v112, v113, v147
	v_max3_f32 v145, v145, v146, v147
	v_mul_f32_e32 v144, v145, v144
	v_mov_b32_e32 v145, v144
	s_nop 1
	v_permlane16_swap_b32_e32 v144, v145
	s_waitcnt lgkmcnt(0)
	v_max_f32_e32 v145, v145, v145
	v_max_f32_e32 v144, v144, v145
	v_mov_b32_e32 v145, v144
	s_nop 1
	v_permlane32_swap_b32_e32 v144, v145
	s_and_saveexec_b64 s[24:25], s[4:5]
	s_cbranch_execz .LBB0_1000
	s_waitcnt lgkmcnt(0)
	v_max_f32_e32 v145, v145, v145
	v_max_f32_e32 v144, v144, v144
	v_max_f32_e32 v144, v144, v145
	ds_write_b32 v210, v144
.LBB0_1000:
	s_or_b64 exec, exec, s[24:25]
	v_or_b32_e32 v144, 16, v142
	s_waitcnt lgkmcnt(0)
	v_ashrrev_i32_e32 v145, 31, v144
	v_lshlrev_b64 v[146:147], 6, v[144:145]
	v_lshl_add_u64 v[160:161], v[136:137], 0, v[146:147]
	s_nop 0
	v_max_f32_e32 v150, v98, v98
	s_waitcnt lgkmcnt(0)
	s_nop 3
	v_max_f32_e32 v148, v110, v110
	v_max_f32_e32 v149, v106, v106
	s_waitcnt lgkmcnt(0)
	s_nop 1
	s_waitcnt lgkmcnt(0)
	s_nop 0
	v_max_f32_e32 v147, v111, v111
	v_max_f32_e32 v147, v148, v147
	v_max_f32_e32 v148, v107, v107
	v_max_f32_e32 v148, v149, v148
	v_max3_f32 v147, v108, v109, v147
	v_max3_f32 v148, v104, v105, v148
	s_nop 0
	v_max3_f32 v147, v147, s2, v148
	v_max_f32_e32 v148, v103, v103
	v_max_f32_e32 v149, v102, v102
	v_max_f32_e32 v148, v149, v148
	v_max_f32_e32 v149, v99, v99
	v_mov_b32_e32 v146, v247
	v_max_f32_e32 v149, v150, v149
	v_max3_f32 v148, v100, v101, v148
	v_max3_f32 v149, v96, v97, v149
	v_max3_f32 v147, v147, v148, v149
	v_mul_f32_e32 v146, v147, v146
	v_mov_b32_e32 v147, v146
	s_nop 1
	v_permlane16_swap_b32_e32 v146, v147
	s_waitcnt lgkmcnt(0)
	v_max_f32_e32 v147, v147, v147
	v_max_f32_e32 v146, v146, v147
	v_mov_b32_e32 v147, v146
	s_nop 1
	v_permlane32_swap_b32_e32 v146, v147
	s_and_saveexec_b64 s[24:25], s[4:5]
	s_cbranch_execz .LBB0_1002
	s_waitcnt lgkmcnt(0)
	v_max_f32_e32 v147, v147, v147
	v_max_f32_e32 v146, v146, v146
	v_max_f32_e32 v146, v146, v147
	ds_write_b32 v210, v146 offset:256
;     __device__ __forceinline__ void operator()(const f32x4 (&acc_)[2][2][4][2], const pg8::Unit& u, int wr, int wc, int fr, int fq) const {
;     ...
;             for (int m = 0; m < 4; ++m) { const float rs = row_rstd(ssq, row0 + ai * 128 + m * 16, fq); float mx = -3.0e38f;
; #pragma unroll
;                 for (int bj = 0; bj < 2; ++bj)
; #pragma unroll
;                     for (int n = 0; n < 2; ++n) { const f32x4 a = acc[ai][bj][m][n]; mx = fmaxf(mx, fmaxf(fmaxf(a[0], a[1]), fmaxf(a[2], a[3]))); }
;                 mx *= rs; mx = fmaxf(mx, __shfl_xor(mx, 16)); mx = fmaxf(mx, __shfl_xor(mx, 32));
;                 if (fq == 0) xch[(lrow0 + ai * 128 + m * 16) * 4 + wc] = mx; }
.LBB0_1002:
	s_or_b64 exec, exec, s[24:25]
	v_or_b32_e32 v146, 32, v142
	s_waitcnt lgkmcnt(0)
	v_ashrrev_i32_e32 v147, 31, v146
	v_lshlrev_b64 v[148:149], 6, v[146:147]
	v_lshl_add_u64 v[162:163], v[136:137], 0, v[148:149]
	s_nop 0
	v_max_f32_e32 v152, v82, v82
	s_waitcnt lgkmcnt(0)
	s_nop 3
	v_max_f32_e32 v150, v94, v94
	v_max_f32_e32 v151, v90, v90
	s_waitcnt lgkmcnt(0)
	s_nop 1
	s_waitcnt lgkmcnt(0)
	s_nop 0
	v_max_f32_e32 v149, v95, v95
	v_max_f32_e32 v149, v150, v149
	v_max_f32_e32 v150, v91, v91
	v_max_f32_e32 v150, v151, v150
	v_max3_f32 v149, v92, v93, v149
	v_max3_f32 v150, v88, v89, v150
	s_nop 0
	v_max3_f32 v149, v149, s2, v150
	v_max_f32_e32 v150, v87, v87
	v_max_f32_e32 v151, v86, v86
	v_max_f32_e32 v150, v151, v150
	v_max_f32_e32 v151, v83, v83
	v_mov_b32_e32 v148, v248
	v_max_f32_e32 v151, v152, v151
	v_max3_f32 v150, v84, v85, v150
	v_max3_f32 v151, v80, v81, v151
	v_max3_f32 v149, v149, v150, v151
	v_mul_f32_e32 v148, v149, v148
	v_mov_b32_e32 v149, v148
	s_nop 1
	v_permlane16_swap_b32_e32 v148, v149
	s_waitcnt lgkmcnt(0)
	v_max_f32_e32 v149, v149, v149
	v_max_f32_e32 v148, v148, v149
	v_mov_b32_e32 v149, v148
	s_nop 1
	v_permlane32_swap_b32_e32 v148, v149
	s_mov_b64 s[24:25], exec
	s_and_b64 s[26:27], s[24:25], s[4:5]
	v_mov_b64_e32 v[242:243], v[196:197]
	v_mov_b64_e32 v[196:197], v[198:199]
	v_mov_b64_e32 v[198:199], v[200:201]
	v_mov_b64_e32 v[200:201], v[178:179]
	s_mov_b64 exec, s[26:27]
	s_cbranch_execz .LBB0_1004
	s_waitcnt lgkmcnt(0)
	v_max_f32_e32 v149, v149, v149
	v_max_f32_e32 v148, v148, v148
	v_max_f32_e32 v148, v148, v149
	ds_write_b32 v210, v148 offset:512
.LBB0_1004:
	s_or_b64 exec, exec, s[24:25]
	v_or_b32_e32 v148, 48, v142
	s_waitcnt lgkmcnt(0)
	v_ashrrev_i32_e32 v149, 31, v148
	v_lshlrev_b64 v[150:151], 6, v[148:149]
	v_lshl_add_u64 v[164:165], v[136:137], 0, v[150:151]
	s_nop 0
	v_max_f32_e32 v154, v66, v66
	s_waitcnt lgkmcnt(0)
	s_nop 3
	v_max_f32_e32 v152, v78, v78
	v_max_f32_e32 v153, v74, v74
	s_waitcnt lgkmcnt(0)
	s_nop 1
	s_waitcnt lgkmcnt(0)
	s_nop 0
	v_max_f32_e32 v151, v79, v79
	v_max_f32_e32 v151, v152, v151
	v_max_f32_e32 v152, v75, v75
	v_max_f32_e32 v152, v153, v152
	v_max3_f32 v151, v76, v77, v151
	v_max3_f32 v152, v72, v73, v152
	s_nop 0
	v_max3_f32 v151, v151, s2, v152
	v_max_f32_e32 v152, v71, v71
	v_max_f32_e32 v153, v70, v70
	v_max_f32_e32 v152, v153, v152
	v_max_f32_e32 v153, v67, v67
	v_mov_b32_e32 v150, v249
	v_max_f32_e32 v153, v154, v153
	v_max3_f32 v152, v68, v69, v152
	v_max3_f32 v153, v64, v65, v153
	v_max3_f32 v151, v151, v152, v153
	v_mul_f32_e32 v150, v151, v150
	v_mov_b32_e32 v151, v150
	s_nop 1
	v_permlane16_swap_b32_e32 v150, v151
	s_waitcnt lgkmcnt(0)
	v_max_f32_e32 v151, v151, v151
	v_max_f32_e32 v150, v150, v151
	v_mov_b32_e32 v151, v150
	s_nop 1
	v_permlane32_swap_b32_e32 v150, v151
	s_and_saveexec_b64 s[24:25], s[4:5]
	s_cbranch_execz .LBB0_1006
	s_waitcnt lgkmcnt(0)
	v_max_f32_e32 v151, v151, v151
	v_max_f32_e32 v150, v150, v150
	v_max_f32_e32 v150, v150, v151
	ds_write_b32 v210, v150 offset:768
.LBB0_1006:
	s_or_b64 exec, exec, s[24:25]
	v_add_u32_e32 v150, 0x80, v142
	s_waitcnt lgkmcnt(0)
	v_ashrrev_i32_e32 v151, 31, v150
	v_lshlrev_b64 v[152:153], 6, v[150:151]
	v_lshl_add_u64 v[166:167], v[136:137], 0, v[152:153]
	s_nop 0
	v_max_f32_e32 v156, v50, v50
	s_waitcnt lgkmcnt(0)
	s_nop 3
	v_max_f32_e32 v154, v62, v62
	v_max_f32_e32 v155, v58, v58
	s_waitcnt lgkmcnt(0)
	s_nop 1
	s_waitcnt lgkmcnt(0)
	s_nop 0
	v_max_f32_e32 v153, v63, v63
	v_max_f32_e32 v153, v154, v153
	v_max_f32_e32 v154, v59, v59
	v_max_f32_e32 v154, v155, v154
	v_max3_f32 v153, v60, v61, v153
	v_max3_f32 v154, v56, v57, v154
	s_nop 0
	v_max3_f32 v153, v153, s2, v154
	v_max_f32_e32 v154, v55, v55
	v_max_f32_e32 v155, v54, v54
	v_max_f32_e32 v154, v155, v154
	v_max_f32_e32 v155, v51, v51
	v_mov_b32_e32 v152, v250
	v_max_f32_e32 v155, v156, v155
	v_max3_f32 v154, v52, v53, v154
	v_max3_f32 v155, v48, v49, v155
	v_max3_f32 v153, v153, v154, v155
	v_mul_f32_e32 v152, v153, v152
	v_mov_b32_e32 v153, v152
	s_nop 1
	v_permlane16_swap_b32_e32 v152, v153
	s_waitcnt lgkmcnt(0)
	v_max_f32_e32 v153, v153, v153
	v_max_f32_e32 v152, v152, v153
	v_mov_b32_e32 v153, v152
	s_nop 1
	v_permlane32_swap_b32_e32 v152, v153
	s_and_saveexec_b64 s[24:25], s[4:5]
	s_cbranch_execz .LBB0_1008
	s_waitcnt lgkmcnt(0)
	v_max_f32_e32 v153, v153, v153
	v_max_f32_e32 v152, v152, v152
	v_max_f32_e32 v152, v152, v153
	ds_write_b32 v210, v152 offset:2048
.LBB0_1008:
	s_or_b64 exec, exec, s[24:25]
	v_add_u32_e32 v152, 0x90, v142
	s_waitcnt lgkmcnt(0)
	v_ashrrev_i32_e32 v153, 31, v152
	v_lshlrev_b64 v[154:155], 6, v[152:153]
	v_lshl_add_u64 v[168:169], v[136:137], 0, v[154:155]
	s_nop 0
	v_max_f32_e32 v170, v34, v34
	s_waitcnt lgkmcnt(0)
	s_nop 3
	v_max_f32_e32 v156, v46, v46
	v_max_f32_e32 v157, v42, v42
	s_waitcnt lgkmcnt(0)
	s_nop 1
	s_waitcnt lgkmcnt(0)
	s_nop 0
	v_max_f32_e32 v155, v47, v47
	v_max_f32_e32 v155, v156, v155
	v_max_f32_e32 v156, v43, v43
	v_max_f32_e32 v156, v157, v156
	v_max3_f32 v155, v44, v45, v155
	v_max3_f32 v156, v40, v41, v156
	s_nop 0
	v_max3_f32 v155, v155, s2, v156
	v_max_f32_e32 v156, v39, v39
	v_max_f32_e32 v157, v38, v38
	v_max_f32_e32 v156, v157, v156
	v_max_f32_e32 v157, v35, v35
	v_mov_b32_e32 v154, v251
	v_max_f32_e32 v157, v170, v157
	v_max3_f32 v156, v36, v37, v156
	v_max3_f32 v157, v32, v33, v157
	v_max3_f32 v155, v155, v156, v157
	v_mul_f32_e32 v154, v155, v154
	v_mov_b32_e32 v155, v154
	s_nop 1
	v_permlane16_swap_b32_e32 v154, v155
	s_waitcnt lgkmcnt(0)
	v_max_f32_e32 v155, v155, v155
	v_max_f32_e32 v154, v154, v155
	v_mov_b32_e32 v155, v154
	s_nop 1
	v_permlane32_swap_b32_e32 v154, v155
	s_and_saveexec_b64 s[24:25], s[4:5]
	s_cbranch_execz .LBB0_1010
	s_waitcnt lgkmcnt(0)
	v_max_f32_e32 v155, v155, v155
	v_max_f32_e32 v154, v154, v154
	v_max_f32_e32 v154, v154, v155
	ds_write_b32 v210, v154 offset:2304
; #define LAS __attribute__((address_space(3)))
;     __device__ __forceinline__ void operator()(const f32x4 (&acc_)[2][2][4][2], const pg8::Unit& u, int wr, int wc, int fr, int fq) const {
;     ...
;             for (int m = 0; m < 4; ++m) { const float rs = row_rstd(ssq, row0 + ai * 128 + m * 16, fq); float mx = -3.0e38f;
; #pragma unroll
;                 for (int bj = 0; bj < 2; ++bj)
; #pragma unroll
;                     for (int n = 0; n < 2; ++n) { const f32x4 a = acc[ai][bj][m][n]; mx = fmaxf(mx, fmaxf(fmaxf(a[0], a[1]), fmaxf(a[2], a[3]))); }
;                 mx *= rs; mx = fmaxf(mx, __shfl_xor(mx, 16)); mx = fmaxf(mx, __shfl_xor(mx, 32));
;                 if (fq == 0) xch[(lrow0 + ai * 128 + m * 16) * 4 + wc] = mx; }
;         asm volatile("s_waitcnt lgkmcnt(0)" ::: "memory"); __builtin_amdgcn_s_barrier(); asm volatile("" ::: "memory");
; #pragma unroll
;         for (int ai = 0; ai < 2; ++ai)
; #pragma unroll
;             for (int m = 0; m < 4; ++m) { const f32x4 x4 = *(const LAS f32x4*)(xch + (lrow0 + ai * 128 + m * 16) * 4); const float mrow = fmaxf(fmaxf(x4[0], x4[1]), fmaxf(x4[2], x4[3])), rs = row_rstd(ssq, row0 + ai * 128 + m * 16, fq); float sm = 0.f;
; #pragma unroll
;                 for (int bj = 0; bj < 2; ++bj)
; #pragma unroll
;                     for (int n = 0; n < 2; ++n) { f32x4 a = acc[ai][bj][m][n];
; #pragma unroll
;                         for (int i = 0; i < 4; ++i) { a[i] = __expf(a[i] * rs - mrow); sm += a[i]; }
;                         asm volatile("" ::: "memory");
;                         acc[ai][bj][m][n] = a; }
;                 sm += __shfl_xor(sm, 16); sm += __shfl_xor(sm, 32);
;                 if (fq == 0) xch[1024 + (lrow0 + ai * 128 + m * 16) * 4 + wc] = sm; }
.LBB0_1010:
	s_or_b64 exec, exec, s[24:25]
	v_add_u32_e32 v154, 0xa0, v142
	s_waitcnt lgkmcnt(0)
	v_ashrrev_i32_e32 v155, 31, v154
	v_lshlrev_b64 v[156:157], 6, v[154:155]
	v_lshl_add_u64 v[170:171], v[136:137], 0, v[156:157]
	s_nop 0
	v_max_f32_e32 v172, v30, v30
	v_max_f32_e32 v173, v26, v26
	v_max_f32_e32 v194, v18, v18
	s_waitcnt lgkmcnt(0)
	s_nop 3
	s_waitcnt lgkmcnt(0)
	s_nop 1
	s_waitcnt lgkmcnt(0)
	s_nop 0
	v_max_f32_e32 v157, v31, v31
	v_max_f32_e32 v157, v172, v157
	v_max_f32_e32 v172, v27, v27
	v_max_f32_e32 v172, v173, v172
	v_max3_f32 v157, v28, v29, v157
	v_max3_f32 v172, v24, v25, v172
	s_nop 0
	v_max3_f32 v157, v157, s2, v172
	v_max_f32_e32 v172, v23, v23
	v_max_f32_e32 v173, v22, v22
	v_max_f32_e32 v172, v173, v172
	v_max_f32_e32 v173, v19, v19
	v_mov_b32_e32 v156, v252
	v_max_f32_e32 v173, v194, v173
	v_max3_f32 v172, v20, v21, v172
	v_max3_f32 v173, v16, v17, v173
	v_max3_f32 v157, v157, v172, v173
	v_mul_f32_e32 v156, v157, v156
	v_mov_b32_e32 v157, v156
	s_nop 1
	v_permlane16_swap_b32_e32 v156, v157
	s_waitcnt lgkmcnt(0)
	v_max_f32_e32 v157, v157, v157
	v_max_f32_e32 v156, v156, v157
	v_mov_b32_e32 v157, v156
	s_nop 1
	v_permlane32_swap_b32_e32 v156, v157
	s_and_saveexec_b64 s[24:25], s[4:5]
	s_cbranch_execz .LBB0_1012
	s_waitcnt lgkmcnt(0)
	v_max_f32_e32 v157, v157, v157
	v_max_f32_e32 v156, v156, v156
	v_max_f32_e32 v156, v156, v157
	ds_write_b32 v210, v156 offset:2560
.LBB0_1012:
	s_or_b64 exec, exec, s[24:25]
	v_add_u32_e32 v156, 0xb0, v142
	s_waitcnt lgkmcnt(0)
	v_ashrrev_i32_e32 v157, 31, v156
	v_lshlrev_b64 v[172:173], 6, v[156:157]
	v_lshl_add_u64 v[172:173], v[136:137], 0, v[172:173]
	s_nop 0
	v_max_f32_e32 v211, v14, v14
	s_waitcnt lgkmcnt(0)
	s_nop 3
	v_max_f32_e32 v218, v10, v10
	v_max_f32_e32 v219, v2, v2
	s_waitcnt lgkmcnt(0)
	s_nop 1
	s_waitcnt lgkmcnt(0)
	s_nop 0
	v_max_f32_e32 v195, v15, v15
	v_max_f32_e32 v195, v211, v195
	v_max_f32_e32 v211, v11, v11
	v_max_f32_e32 v211, v218, v211
	v_max3_f32 v195, v12, v13, v195
	v_max3_f32 v211, v8, v9, v211
	s_nop 0
	v_max3_f32 v195, v195, s2, v211
	v_max_f32_e32 v211, v7, v7
	v_max_f32_e32 v218, v6, v6
	v_max_f32_e32 v211, v218, v211
	v_max_f32_e32 v218, v3, v3
	v_mov_b32_e32 v194, v253
	v_max_f32_e32 v218, v219, v218
	v_max3_f32 v211, v4, v5, v211
	v_max3_f32 v218, v0, v1, v218
	v_max3_f32 v195, v195, v211, v218
	v_mul_f32_e32 v194, v195, v194
	v_mov_b32_e32 v195, v194
	s_nop 1
	v_permlane16_swap_b32_e32 v194, v195
	s_waitcnt lgkmcnt(0)
	v_max_f32_e32 v195, v195, v195
	v_max_f32_e32 v211, v194, v195
	ds_bpermute_b32 v218, v208, v211
	s_and_saveexec_b64 s[24:25], s[4:5]
	s_cbranch_execz .LBB0_1014
	s_waitcnt lgkmcnt(0)
	v_max_f32_e32 v194, v218, v218
	v_max_f32_e32 v195, v211, v211
	v_max_f32_e32 v194, v195, v194
	ds_write_b32 v210, v194 offset:2816
.LBB0_1014:
	s_or_b64 exec, exec, s[24:25]
	s_waitcnt lgkmcnt(0)
	s_barrier
	s_waitcnt lgkmcnt(0)
	s_nop 0
	s_waitcnt lgkmcnt(0)
	s_nop 3
	ds_read_b128 v[218:221], v180
	s_nop 1
	s_waitcnt lgkmcnt(0)
	v_max_f32_e32 v194, v221, v221
	s_waitcnt lgkmcnt(0)
	s_nop 1
	s_waitcnt lgkmcnt(0)
	s_nop 1
	v_mov_b32_e32 v158, v246
	v_max_f32_e32 v159, v220, v220
	v_max_f32_e32 v159, v159, v194
	v_max3_f32 v159, v218, v219, v159
	v_fma_f32 v124, v124, v158, -v159
	v_fma_f32 v125, v125, v158, -v159
	v_fma_f32 v122, v122, v158, -v159
	v_mul_f32_e32 v124, 0x3fb8aa3b, v124
	v_fma_f32 v126, v126, v158, -v159
	v_fma_f32 v127, v127, v158, -v159
	v_fma_f32 v120, v120, v158, -v159
	v_fma_f32 v121, v121, v158, -v159
	v_fma_f32 v123, v123, v158, -v159
	v_fma_f32 v116, v116, v158, -v159
	v_fma_f32 v117, v117, v158, -v159
	v_fma_f32 v118, v118, v158, -v159
	v_fma_f32 v119, v119, v158, -v159
	v_fma_f32 v112, v112, v158, -v159
	v_fma_f32 v113, v113, v158, -v159
	v_fma_f32 v114, v114, v158, -v159
	v_fma_f32 v115, v115, v158, -v159
	v_mul_f32_e32 v125, 0x3fb8aa3b, v125
	v_mul_f32_e32 v158, 0x3fb8aa3b, v122
	v_exp_f32_e32 v122, v124
	v_mul_f32_e32 v126, 0x3fb8aa3b, v126
	v_mul_f32_e32 v159, 0x3fb8aa3b, v123
	v_exp_f32_e32 v123, v125
	v_mul_f32_e32 v127, 0x3fb8aa3b, v127
	v_exp_f32_e32 v126, v126
	v_mul_f32_e32 v120, 0x3fb8aa3b, v120
	v_mul_f32_e32 v117, 0x3fb8aa3b, v117
	v_exp_f32_e32 v127, v127
	v_mul_f32_e32 v121, 0x3fb8aa3b, v121
	v_mul_f32_e32 v195, 0x3fb8aa3b, v115
	v_exp_f32_e32 v120, v120
	v_exp_f32_e32 v115, v117
	v_add_f32_e32 v117, 0, v122
	v_exp_f32_e32 v121, v121
	v_add_f32_e32 v117, v123, v117
	v_exp_f32_e32 v124, v158
	v_add_f32_e32 v117, v126, v117
	v_mul_f32_e32 v116, 0x3fb8aa3b, v116
	v_exp_f32_e32 v125, v159
	v_add_f32_e32 v117, v127, v117
	v_mul_f32_e32 v194, 0x3fb8aa3b, v114
	v_exp_f32_e32 v114, v116
	v_add_f32_e32 v117, v120, v117
	v_mul_f32_e32 v118, 0x3fb8aa3b, v118
	v_add_f32_e32 v117, v121, v117
	v_mul_f32_e32 v119, 0x3fb8aa3b, v119
	v_exp_f32_e32 v118, v118
	v_add_f32_e32 v117, v124, v117
	v_mul_f32_e32 v112, 0x3fb8aa3b, v112
	v_exp_f32_e32 v119, v119
	v_add_f32_e32 v117, v125, v117
	v_mul_f32_e32 v113, 0x3fb8aa3b, v113
	v_exp_f32_e32 v112, v112
	v_add_f32_e32 v117, v114, v117
	v_exp_f32_e32 v113, v113
	v_add_f32_e32 v117, v115, v117
	v_exp_f32_e32 v116, v194
	v_add_f32_e32 v117, v118, v117
	v_add_f32_e32 v158, v119, v117
	v_exp_f32_e32 v117, v195
	v_add_f32_e32 v158, v112, v158
	v_add_f32_e32 v158, v113, v158
	v_add_f32_e32 v158, v116, v158
	v_add_f32_e32 v158, v117, v158
	v_mov_b32_e32 v159, v158
	s_nop 1
	v_permlane16_swap_b32_e32 v158, v159
	s_waitcnt lgkmcnt(0)
	v_add_f32_e32 v158, v158, v159
	v_mov_b32_e32 v159, v158
	s_nop 1
	v_permlane32_swap_b32_e32 v158, v159
	s_and_saveexec_b64 s[24:25], s[4:5]
	s_cbranch_execz .LBB0_1016
	s_waitcnt lgkmcnt(0)
	v_add_f32_e32 v158, v158, v159
	ds_write_b32 v181, v158 offset:4096
; #define LAS __attribute__((address_space(3)))
;     __device__ __forceinline__ void operator()(const f32x4 (&acc_)[2][2][4][2], const pg8::Unit& u, int wr, int wc, int fr, int fq) const {
;     ...
;             for (int m = 0; m < 4; ++m) { const f32x4 x4 = *(const LAS f32x4*)(xch + (lrow0 + ai * 128 + m * 16) * 4); const float mrow = fmaxf(fmaxf(x4[0], x4[1]), fmaxf(x4[2], x4[3])), rs = row_rstd(ssq, row0 + ai * 128 + m * 16, fq); float sm = 0.f;
; #pragma unroll
;                 for (int bj = 0; bj < 2; ++bj)
; #pragma unroll
;                     for (int n = 0; n < 2; ++n) { f32x4 a = acc[ai][bj][m][n];
; #pragma unroll
;                         for (int i = 0; i < 4; ++i) { a[i] = __expf(a[i] * rs - mrow); sm += a[i]; }
;                         asm volatile("" ::: "memory");
;                         acc[ai][bj][m][n] = a; }
;                 sm += __shfl_xor(sm, 16); sm += __shfl_xor(sm, 32);
;                 if (fq == 0) xch[1024 + (lrow0 + ai * 128 + m * 16) * 4 + wc] = sm; }
.LBB0_1016:
	s_or_b64 exec, exec, s[24:25]
	s_waitcnt lgkmcnt(0)
	s_nop 0
	s_waitcnt lgkmcnt(0)
	s_nop 3
	s_nop 0
	s_nop 1
	ds_read_b128 v[158:161], v182
	s_waitcnt lgkmcnt(0)
	s_nop 1
	s_waitcnt lgkmcnt(0)
	v_max_f32_e32 v161, v161, v161
	v_max_f32_e32 v160, v160, v160
	v_max_f32_e32 v160, v160, v161
	v_max3_f32 v158, v158, v159, v160
	s_waitcnt lgkmcnt(0)
	s_nop 1
	v_mov_b32_e32 v194, v247
	s_nop 0
	v_fma_f32 v108, v108, v194, -v158
	v_fma_f32 v109, v109, v194, -v158
	v_fma_f32 v106, v106, v194, -v158
	v_mul_f32_e32 v108, 0x3fb8aa3b, v108
	v_fma_f32 v110, v110, v194, -v158
	v_fma_f32 v111, v111, v194, -v158
	v_fma_f32 v104, v104, v194, -v158
	v_fma_f32 v105, v105, v194, -v158
	v_fma_f32 v107, v107, v194, -v158
	v_fma_f32 v100, v100, v194, -v158
	v_fma_f32 v101, v101, v194, -v158
	v_fma_f32 v102, v102, v194, -v158
	v_fma_f32 v103, v103, v194, -v158
	v_fma_f32 v96, v96, v194, -v158
	v_fma_f32 v97, v97, v194, -v158
	v_fma_f32 v98, v98, v194, -v158
	v_fma_f32 v99, v99, v194, -v158
	v_mul_f32_e32 v109, 0x3fb8aa3b, v109
	v_mul_f32_e32 v158, 0x3fb8aa3b, v106
	v_exp_f32_e32 v106, v108
	v_mul_f32_e32 v110, 0x3fb8aa3b, v110
	v_mul_f32_e32 v159, 0x3fb8aa3b, v107
	v_exp_f32_e32 v107, v109
	v_mul_f32_e32 v111, 0x3fb8aa3b, v111
	v_exp_f32_e32 v110, v110
	v_mul_f32_e32 v104, 0x3fb8aa3b, v104
	v_mul_f32_e32 v101, 0x3fb8aa3b, v101
	v_exp_f32_e32 v111, v111
	v_mul_f32_e32 v105, 0x3fb8aa3b, v105
	v_mul_f32_e32 v161, 0x3fb8aa3b, v99
	v_exp_f32_e32 v104, v104
	v_exp_f32_e32 v99, v101
	v_add_f32_e32 v101, 0, v106
	v_exp_f32_e32 v105, v105
	v_add_f32_e32 v101, v107, v101
	v_exp_f32_e32 v108, v158
	v_add_f32_e32 v101, v110, v101
	v_mul_f32_e32 v100, 0x3fb8aa3b, v100
	v_exp_f32_e32 v109, v159
	v_add_f32_e32 v101, v111, v101
	v_mul_f32_e32 v160, 0x3fb8aa3b, v98
	v_exp_f32_e32 v98, v100
	v_add_f32_e32 v101, v104, v101
	v_mul_f32_e32 v102, 0x3fb8aa3b, v102
	v_add_f32_e32 v101, v105, v101
	v_mul_f32_e32 v103, 0x3fb8aa3b, v103
	v_exp_f32_e32 v102, v102
	v_add_f32_e32 v101, v108, v101
	v_mul_f32_e32 v96, 0x3fb8aa3b, v96
	v_exp_f32_e32 v103, v103
	v_add_f32_e32 v101, v109, v101
	v_mul_f32_e32 v97, 0x3fb8aa3b, v97
	v_exp_f32_e32 v96, v96
	v_add_f32_e32 v101, v98, v101
	v_exp_f32_e32 v97, v97
	v_add_f32_e32 v101, v99, v101
	v_exp_f32_e32 v100, v160
	v_add_f32_e32 v101, v102, v101
	v_add_f32_e32 v158, v103, v101
	v_exp_f32_e32 v101, v161
	v_add_f32_e32 v158, v96, v158
	v_add_f32_e32 v158, v97, v158
	v_add_f32_e32 v158, v100, v158
	v_add_f32_e32 v158, v101, v158
	v_mov_b32_e32 v159, v158
	s_nop 1
	v_permlane16_swap_b32_e32 v158, v159
	s_waitcnt lgkmcnt(0)
	v_add_f32_e32 v158, v158, v159
	v_mov_b32_e32 v159, v158
	s_nop 1
	v_permlane32_swap_b32_e32 v158, v159
	s_and_saveexec_b64 s[24:25], s[4:5]
	s_cbranch_execz .LBB0_1018
	s_waitcnt lgkmcnt(0)
	v_add_f32_e32 v158, v158, v159
	ds_write_b32 v183, v158 offset:4096
.LBB0_1018:
	s_or_b64 exec, exec, s[24:25]
	s_waitcnt lgkmcnt(0)
	s_nop 0
	s_waitcnt lgkmcnt(0)
	s_nop 3
	s_nop 0
	s_nop 1
	ds_read_b128 v[158:161], v184
	s_waitcnt lgkmcnt(0)
	s_nop 1
	s_waitcnt lgkmcnt(0)
	v_max_f32_e32 v161, v161, v161
	v_max_f32_e32 v160, v160, v160
	v_max_f32_e32 v160, v160, v161
	v_max3_f32 v158, v158, v159, v160
	s_waitcnt lgkmcnt(0)
	s_nop 1
	v_mov_b32_e32 v162, v248
	s_nop 0
	v_fma_f32 v92, v92, v162, -v158
	v_fma_f32 v93, v93, v162, -v158
	v_fma_f32 v90, v90, v162, -v158
	v_mul_f32_e32 v92, 0x3fb8aa3b, v92
	v_fma_f32 v94, v94, v162, -v158
	v_fma_f32 v95, v95, v162, -v158
	v_fma_f32 v88, v88, v162, -v158
	v_fma_f32 v89, v89, v162, -v158
	v_fma_f32 v91, v91, v162, -v158
	v_fma_f32 v84, v84, v162, -v158
	v_fma_f32 v85, v85, v162, -v158
	v_fma_f32 v86, v86, v162, -v158
	v_fma_f32 v87, v87, v162, -v158
	v_fma_f32 v80, v80, v162, -v158
	v_fma_f32 v81, v81, v162, -v158
	v_fma_f32 v82, v82, v162, -v158
	v_fma_f32 v83, v83, v162, -v158
	v_mul_f32_e32 v93, 0x3fb8aa3b, v93
	v_mul_f32_e32 v158, 0x3fb8aa3b, v90
	v_exp_f32_e32 v90, v92
	v_mul_f32_e32 v94, 0x3fb8aa3b, v94
	v_mul_f32_e32 v159, 0x3fb8aa3b, v91
	v_exp_f32_e32 v91, v93
	v_mul_f32_e32 v95, 0x3fb8aa3b, v95
	v_exp_f32_e32 v94, v94
	v_mul_f32_e32 v88, 0x3fb8aa3b, v88
	v_mul_f32_e32 v85, 0x3fb8aa3b, v85
	v_exp_f32_e32 v95, v95
	v_mul_f32_e32 v89, 0x3fb8aa3b, v89
	v_mul_f32_e32 v161, 0x3fb8aa3b, v83
	v_exp_f32_e32 v88, v88
	v_exp_f32_e32 v83, v85
	v_add_f32_e32 v85, 0, v90
	v_exp_f32_e32 v89, v89
	v_add_f32_e32 v85, v91, v85
	v_exp_f32_e32 v92, v158
	v_add_f32_e32 v85, v94, v85
	v_mul_f32_e32 v84, 0x3fb8aa3b, v84
	v_exp_f32_e32 v93, v159
	v_add_f32_e32 v85, v95, v85
	v_mul_f32_e32 v160, 0x3fb8aa3b, v82
	v_exp_f32_e32 v82, v84
	v_add_f32_e32 v85, v88, v85
	v_mul_f32_e32 v86, 0x3fb8aa3b, v86
	v_add_f32_e32 v85, v89, v85
	v_mul_f32_e32 v87, 0x3fb8aa3b, v87
	v_exp_f32_e32 v86, v86
	v_add_f32_e32 v85, v92, v85
	v_mul_f32_e32 v80, 0x3fb8aa3b, v80
	v_exp_f32_e32 v87, v87
	v_add_f32_e32 v85, v93, v85
	v_mul_f32_e32 v81, 0x3fb8aa3b, v81
	v_exp_f32_e32 v80, v80
	v_add_f32_e32 v85, v82, v85
	v_exp_f32_e32 v81, v81
	v_add_f32_e32 v85, v83, v85
	v_exp_f32_e32 v84, v160
	v_add_f32_e32 v85, v86, v85
	v_add_f32_e32 v158, v87, v85
	v_exp_f32_e32 v85, v161
	v_add_f32_e32 v158, v80, v158
	v_add_f32_e32 v158, v81, v158
	v_add_f32_e32 v158, v84, v158
	v_add_f32_e32 v158, v85, v158
	v_mov_b32_e32 v159, v158
	s_nop 1
	v_permlane16_swap_b32_e32 v158, v159
	s_waitcnt lgkmcnt(0)
	v_add_f32_e32 v158, v158, v159
	v_mov_b32_e32 v159, v158
	s_nop 1
	v_permlane32_swap_b32_e32 v158, v159
	s_and_saveexec_b64 s[24:25], s[4:5]
	s_cbranch_execz .LBB0_1020
	s_waitcnt lgkmcnt(0)
	v_add_f32_e32 v158, v158, v159
	ds_write_b32 v185, v158 offset:4096
; #define LAS __attribute__((address_space(3)))
;     __device__ __forceinline__ void operator()(const f32x4 (&acc_)[2][2][4][2], const pg8::Unit& u, int wr, int wc, int fr, int fq) const {
;     ...
;             for (int m = 0; m < 4; ++m) { const f32x4 x4 = *(const LAS f32x4*)(xch + (lrow0 + ai * 128 + m * 16) * 4); const float mrow = fmaxf(fmaxf(x4[0], x4[1]), fmaxf(x4[2], x4[3])), rs = row_rstd(ssq, row0 + ai * 128 + m * 16, fq); float sm = 0.f;
; #pragma unroll
;                 for (int bj = 0; bj < 2; ++bj)
; #pragma unroll
;                     for (int n = 0; n < 2; ++n) { f32x4 a = acc[ai][bj][m][n];
; #pragma unroll
;                         for (int i = 0; i < 4; ++i) { a[i] = __expf(a[i] * rs - mrow); sm += a[i]; }
;                         asm volatile("" ::: "memory");
;                         acc[ai][bj][m][n] = a; }
;                 sm += __shfl_xor(sm, 16); sm += __shfl_xor(sm, 32);
;                 if (fq == 0) xch[1024 + (lrow0 + ai * 128 + m * 16) * 4 + wc] = sm; }
.LBB0_1020:
	s_or_b64 exec, exec, s[24:25]
	s_waitcnt lgkmcnt(0)
	s_nop 0
	s_waitcnt lgkmcnt(0)
	s_nop 3
	s_nop 0
	s_nop 1
	ds_read_b128 v[158:161], v186
	s_waitcnt lgkmcnt(0)
	s_nop 1
	s_waitcnt lgkmcnt(0)
	v_max_f32_e32 v161, v161, v161
	v_max_f32_e32 v160, v160, v160
	v_max_f32_e32 v160, v160, v161
	v_max3_f32 v158, v158, v159, v160
	s_waitcnt lgkmcnt(0)
	s_nop 1
	v_mov_b32_e32 v162, v249
	s_nop 0
	v_fma_f32 v76, v76, v162, -v158
	v_fma_f32 v77, v77, v162, -v158
	v_fma_f32 v74, v74, v162, -v158
	v_mul_f32_e32 v76, 0x3fb8aa3b, v76
	v_fma_f32 v78, v78, v162, -v158
	v_fma_f32 v79, v79, v162, -v158
	v_fma_f32 v72, v72, v162, -v158
	v_fma_f32 v73, v73, v162, -v158
	v_fma_f32 v75, v75, v162, -v158
	v_fma_f32 v68, v68, v162, -v158
	v_fma_f32 v69, v69, v162, -v158
	v_fma_f32 v70, v70, v162, -v158
	v_fma_f32 v71, v71, v162, -v158
	v_fma_f32 v64, v64, v162, -v158
	v_fma_f32 v65, v65, v162, -v158
	v_fma_f32 v66, v66, v162, -v158
	v_fma_f32 v67, v67, v162, -v158
	v_mul_f32_e32 v77, 0x3fb8aa3b, v77
	v_mul_f32_e32 v158, 0x3fb8aa3b, v74
	v_exp_f32_e32 v74, v76
	v_mul_f32_e32 v78, 0x3fb8aa3b, v78
	v_mul_f32_e32 v159, 0x3fb8aa3b, v75
	v_exp_f32_e32 v75, v77
	v_mul_f32_e32 v79, 0x3fb8aa3b, v79
	v_exp_f32_e32 v78, v78
	v_mul_f32_e32 v72, 0x3fb8aa3b, v72
	v_mul_f32_e32 v69, 0x3fb8aa3b, v69
	v_exp_f32_e32 v79, v79
	v_mul_f32_e32 v73, 0x3fb8aa3b, v73
	v_mul_f32_e32 v161, 0x3fb8aa3b, v67
	v_exp_f32_e32 v72, v72
	v_exp_f32_e32 v67, v69
	v_add_f32_e32 v69, 0, v74
	v_exp_f32_e32 v73, v73
	v_add_f32_e32 v69, v75, v69
	v_exp_f32_e32 v76, v158
	v_add_f32_e32 v69, v78, v69
	v_mul_f32_e32 v68, 0x3fb8aa3b, v68
	v_exp_f32_e32 v77, v159
	v_add_f32_e32 v69, v79, v69
	v_mul_f32_e32 v160, 0x3fb8aa3b, v66
	v_exp_f32_e32 v66, v68
	v_add_f32_e32 v69, v72, v69
	v_mul_f32_e32 v70, 0x3fb8aa3b, v70
	v_add_f32_e32 v69, v73, v69
	v_mul_f32_e32 v71, 0x3fb8aa3b, v71
	v_exp_f32_e32 v70, v70
	v_add_f32_e32 v69, v76, v69
	v_mul_f32_e32 v64, 0x3fb8aa3b, v64
	v_exp_f32_e32 v71, v71
	v_add_f32_e32 v69, v77, v69
	v_mul_f32_e32 v65, 0x3fb8aa3b, v65
	v_exp_f32_e32 v64, v64
	v_add_f32_e32 v69, v66, v69
	v_exp_f32_e32 v65, v65
	v_add_f32_e32 v69, v67, v69
	v_exp_f32_e32 v68, v160
	v_add_f32_e32 v69, v70, v69
	v_add_f32_e32 v158, v71, v69
	v_exp_f32_e32 v69, v161
	v_add_f32_e32 v158, v64, v158
	v_add_f32_e32 v158, v65, v158
	v_add_f32_e32 v158, v68, v158
	v_add_f32_e32 v158, v69, v158
	v_mov_b32_e32 v159, v158
	s_nop 1
	v_permlane16_swap_b32_e32 v158, v159
	s_waitcnt lgkmcnt(0)
	v_add_f32_e32 v158, v158, v159
	v_mov_b32_e32 v159, v158
	s_nop 1
	v_permlane32_swap_b32_e32 v158, v159
	s_and_saveexec_b64 s[24:25], s[4:5]
	s_cbranch_execz .LBB0_1022
	s_waitcnt lgkmcnt(0)
	v_add_f32_e32 v158, v158, v159
	ds_write_b32 v187, v158 offset:4096
.LBB0_1022:
	s_or_b64 exec, exec, s[24:25]
	s_waitcnt lgkmcnt(0)
	s_nop 0
	s_waitcnt lgkmcnt(0)
	s_nop 3
	s_nop 0
	s_nop 1
	ds_read_b128 v[158:161], v188
	s_waitcnt lgkmcnt(0)
	s_nop 1
	s_waitcnt lgkmcnt(0)
	v_max_f32_e32 v161, v161, v161
	v_max_f32_e32 v160, v160, v160
	v_max_f32_e32 v160, v160, v161
	v_max3_f32 v158, v158, v159, v160
	s_waitcnt lgkmcnt(0)
	s_nop 1
	v_mov_b32_e32 v162, v250
	s_nop 0
	v_fma_f32 v60, v60, v162, -v158
	v_fma_f32 v61, v61, v162, -v158
	v_fma_f32 v58, v58, v162, -v158
	v_mul_f32_e32 v60, 0x3fb8aa3b, v60
	v_fma_f32 v62, v62, v162, -v158
	v_fma_f32 v63, v63, v162, -v158
	v_fma_f32 v56, v56, v162, -v158
	v_fma_f32 v57, v57, v162, -v158
	v_fma_f32 v59, v59, v162, -v158
	v_fma_f32 v52, v52, v162, -v158
	v_fma_f32 v53, v53, v162, -v158
	v_fma_f32 v54, v54, v162, -v158
	v_fma_f32 v55, v55, v162, -v158
	v_fma_f32 v48, v48, v162, -v158
	v_fma_f32 v49, v49, v162, -v158
	v_fma_f32 v50, v50, v162, -v158
	v_fma_f32 v51, v51, v162, -v158
	v_mul_f32_e32 v61, 0x3fb8aa3b, v61
	v_mul_f32_e32 v158, 0x3fb8aa3b, v58
	v_exp_f32_e32 v58, v60
	v_mul_f32_e32 v62, 0x3fb8aa3b, v62
	v_mul_f32_e32 v159, 0x3fb8aa3b, v59
	v_exp_f32_e32 v59, v61
	v_mul_f32_e32 v63, 0x3fb8aa3b, v63
	v_exp_f32_e32 v62, v62
	v_mul_f32_e32 v56, 0x3fb8aa3b, v56
	v_mul_f32_e32 v53, 0x3fb8aa3b, v53
	v_exp_f32_e32 v63, v63
	v_mul_f32_e32 v57, 0x3fb8aa3b, v57
	v_mul_f32_e32 v161, 0x3fb8aa3b, v51
	v_exp_f32_e32 v56, v56
	v_exp_f32_e32 v51, v53
	v_add_f32_e32 v53, 0, v58
	v_exp_f32_e32 v57, v57
	v_add_f32_e32 v53, v59, v53
	v_exp_f32_e32 v60, v158
	v_add_f32_e32 v53, v62, v53
	v_mul_f32_e32 v52, 0x3fb8aa3b, v52
	v_exp_f32_e32 v61, v159
	v_add_f32_e32 v53, v63, v53
	v_mul_f32_e32 v160, 0x3fb8aa3b, v50
	v_exp_f32_e32 v50, v52
	v_add_f32_e32 v53, v56, v53
	v_mul_f32_e32 v54, 0x3fb8aa3b, v54
	v_add_f32_e32 v53, v57, v53
	v_mul_f32_e32 v55, 0x3fb8aa3b, v55
	v_exp_f32_e32 v54, v54
	v_add_f32_e32 v53, v60, v53
	v_mul_f32_e32 v48, 0x3fb8aa3b, v48
	v_exp_f32_e32 v55, v55
	v_add_f32_e32 v53, v61, v53
	v_mul_f32_e32 v49, 0x3fb8aa3b, v49
	v_exp_f32_e32 v48, v48
	v_add_f32_e32 v53, v50, v53
	v_exp_f32_e32 v49, v49
	v_add_f32_e32 v53, v51, v53
	v_exp_f32_e32 v52, v160
	v_add_f32_e32 v53, v54, v53
	v_add_f32_e32 v158, v55, v53
	v_exp_f32_e32 v53, v161
	v_add_f32_e32 v158, v48, v158
	v_add_f32_e32 v158, v49, v158
	v_add_f32_e32 v158, v52, v158
	v_add_f32_e32 v158, v53, v158
	v_mov_b32_e32 v159, v158
	s_nop 1
	v_permlane16_swap_b32_e32 v158, v159
	s_waitcnt lgkmcnt(0)
	v_add_f32_e32 v158, v158, v159
	v_mov_b32_e32 v159, v158
	s_nop 1
	v_permlane32_swap_b32_e32 v158, v159
	s_and_saveexec_b64 s[24:25], s[4:5]
	s_cbranch_execz .LBB0_1024
	s_waitcnt lgkmcnt(0)
	v_add_f32_e32 v158, v158, v159
	ds_write_b32 v189, v158 offset:4096
; #define LAS __attribute__((address_space(3)))
;     __device__ __forceinline__ void operator()(const f32x4 (&acc_)[2][2][4][2], const pg8::Unit& u, int wr, int wc, int fr, int fq) const {
;     ...
;             for (int m = 0; m < 4; ++m) { const f32x4 x4 = *(const LAS f32x4*)(xch + (lrow0 + ai * 128 + m * 16) * 4); const float mrow = fmaxf(fmaxf(x4[0], x4[1]), fmaxf(x4[2], x4[3])), rs = row_rstd(ssq, row0 + ai * 128 + m * 16, fq); float sm = 0.f;
; #pragma unroll
;                 for (int bj = 0; bj < 2; ++bj)
; #pragma unroll
;                     for (int n = 0; n < 2; ++n) { f32x4 a = acc[ai][bj][m][n];
; #pragma unroll
;                         for (int i = 0; i < 4; ++i) { a[i] = __expf(a[i] * rs - mrow); sm += a[i]; }
;                         asm volatile("" ::: "memory");
;                         acc[ai][bj][m][n] = a; }
;                 sm += __shfl_xor(sm, 16); sm += __shfl_xor(sm, 32);
;                 if (fq == 0) xch[1024 + (lrow0 + ai * 128 + m * 16) * 4 + wc] = sm; }
.LBB0_1024:
	s_or_b64 exec, exec, s[24:25]
	s_waitcnt lgkmcnt(0)
	s_nop 0
	s_waitcnt lgkmcnt(0)
	s_nop 3
	s_nop 0
	s_nop 1
	ds_read_b128 v[158:161], v190
	s_waitcnt lgkmcnt(0)
	s_nop 1
	s_waitcnt lgkmcnt(0)
	v_max_f32_e32 v161, v161, v161
	v_max_f32_e32 v160, v160, v160
	v_max_f32_e32 v160, v160, v161
	v_max3_f32 v158, v158, v159, v160
	s_waitcnt lgkmcnt(0)
	s_nop 1
	v_mov_b32_e32 v162, v251
	s_nop 0
	v_fma_f32 v44, v44, v162, -v158
	v_fma_f32 v45, v45, v162, -v158
	v_fma_f32 v42, v42, v162, -v158
	v_mul_f32_e32 v44, 0x3fb8aa3b, v44
	v_fma_f32 v46, v46, v162, -v158
	v_fma_f32 v47, v47, v162, -v158
	v_fma_f32 v40, v40, v162, -v158
	v_fma_f32 v41, v41, v162, -v158
	v_fma_f32 v43, v43, v162, -v158
	v_fma_f32 v36, v36, v162, -v158
	v_fma_f32 v37, v37, v162, -v158
	v_fma_f32 v38, v38, v162, -v158
	v_fma_f32 v39, v39, v162, -v158
	v_fma_f32 v32, v32, v162, -v158
	v_fma_f32 v33, v33, v162, -v158
	v_fma_f32 v34, v34, v162, -v158
	v_fma_f32 v35, v35, v162, -v158
	v_mul_f32_e32 v45, 0x3fb8aa3b, v45
	v_mul_f32_e32 v158, 0x3fb8aa3b, v42
	v_exp_f32_e32 v42, v44
	v_mul_f32_e32 v46, 0x3fb8aa3b, v46
	v_mul_f32_e32 v159, 0x3fb8aa3b, v43
	v_exp_f32_e32 v43, v45
	v_mul_f32_e32 v47, 0x3fb8aa3b, v47
	v_exp_f32_e32 v46, v46
	v_mul_f32_e32 v40, 0x3fb8aa3b, v40
	v_mul_f32_e32 v37, 0x3fb8aa3b, v37
	v_exp_f32_e32 v47, v47
	v_mul_f32_e32 v41, 0x3fb8aa3b, v41
	v_mul_f32_e32 v161, 0x3fb8aa3b, v35
	v_exp_f32_e32 v40, v40
	v_exp_f32_e32 v35, v37
	v_add_f32_e32 v37, 0, v42
	v_exp_f32_e32 v41, v41
	v_add_f32_e32 v37, v43, v37
	v_exp_f32_e32 v44, v158
	v_add_f32_e32 v37, v46, v37
	v_mul_f32_e32 v36, 0x3fb8aa3b, v36
	v_exp_f32_e32 v45, v159
	v_add_f32_e32 v37, v47, v37
	v_mul_f32_e32 v160, 0x3fb8aa3b, v34
	v_exp_f32_e32 v34, v36
	v_add_f32_e32 v37, v40, v37
	v_mul_f32_e32 v38, 0x3fb8aa3b, v38
	v_add_f32_e32 v37, v41, v37
	v_mul_f32_e32 v39, 0x3fb8aa3b, v39
	v_exp_f32_e32 v38, v38
	v_add_f32_e32 v37, v44, v37
	v_mul_f32_e32 v32, 0x3fb8aa3b, v32
	v_exp_f32_e32 v39, v39
	v_add_f32_e32 v37, v45, v37
	v_mul_f32_e32 v33, 0x3fb8aa3b, v33
	v_exp_f32_e32 v32, v32
	v_add_f32_e32 v37, v34, v37
	v_exp_f32_e32 v33, v33
	v_add_f32_e32 v37, v35, v37
	v_exp_f32_e32 v36, v160
	v_add_f32_e32 v37, v38, v37
	v_add_f32_e32 v158, v39, v37
	v_exp_f32_e32 v37, v161
	v_add_f32_e32 v158, v32, v158
	v_add_f32_e32 v158, v33, v158
	v_add_f32_e32 v158, v36, v158
	v_add_f32_e32 v158, v37, v158
	v_mov_b32_e32 v159, v158
	s_nop 1
	v_permlane16_swap_b32_e32 v158, v159
	s_waitcnt lgkmcnt(0)
	v_add_f32_e32 v158, v158, v159
	v_mov_b32_e32 v159, v158
	s_nop 1
	v_permlane32_swap_b32_e32 v158, v159
	s_and_saveexec_b64 s[24:25], s[4:5]
	s_cbranch_execz .LBB0_1026
	s_waitcnt lgkmcnt(0)
	v_add_f32_e32 v158, v158, v159
	ds_write_b32 v191, v158 offset:4096
; #define LAS __attribute__((address_space(3)))
;     __device__ __forceinline__ void operator()(const f32x4 (&acc_)[2][2][4][2], const pg8::Unit& u, int wr, int wc, int fr, int fq) const {
;     ...
;             for (int m = 0; m < 4; ++m) { const f32x4 x4 = *(const LAS f32x4*)(xch + (lrow0 + ai * 128 + m * 16) * 4); const float mrow = fmaxf(fmaxf(x4[0], x4[1]), fmaxf(x4[2], x4[3])), rs = row_rstd(ssq, row0 + ai * 128 + m * 16, fq); float sm = 0.f;
; #pragma unroll
;                 for (int bj = 0; bj < 2; ++bj)
; #pragma unroll
;                     for (int n = 0; n < 2; ++n) { f32x4 a = acc[ai][bj][m][n];
; #pragma unroll
;                         for (int i = 0; i < 4; ++i) { a[i] = __expf(a[i] * rs - mrow); sm += a[i]; }
;                         asm volatile("" ::: "memory");
;                         acc[ai][bj][m][n] = a; }
;                 sm += __shfl_xor(sm, 16); sm += __shfl_xor(sm, 32);
;                 if (fq == 0) xch[1024 + (lrow0 + ai * 128 + m * 16) * 4 + wc] = sm; }
.LBB0_1026:
	s_or_b64 exec, exec, s[24:25]
	s_waitcnt lgkmcnt(0)
	s_nop 0
	s_waitcnt lgkmcnt(0)
	s_nop 3
	s_nop 0
	s_nop 1
	ds_read_b128 v[158:161], v202
	s_waitcnt lgkmcnt(0)
	s_nop 1
	s_waitcnt lgkmcnt(0)
	v_max_f32_e32 v161, v161, v161
	v_max_f32_e32 v160, v160, v160
	v_max_f32_e32 v160, v160, v161
	v_max3_f32 v158, v158, v159, v160
	s_waitcnt lgkmcnt(0)
	s_nop 1
	v_mov_b32_e32 v162, v252
	s_nop 0
	v_fma_f32 v28, v28, v162, -v158
	v_fma_f32 v29, v29, v162, -v158
	v_fma_f32 v26, v26, v162, -v158
	v_mul_f32_e32 v28, 0x3fb8aa3b, v28
	v_fma_f32 v30, v30, v162, -v158
	v_fma_f32 v31, v31, v162, -v158
	v_fma_f32 v24, v24, v162, -v158
	v_fma_f32 v25, v25, v162, -v158
	v_fma_f32 v27, v27, v162, -v158
	v_fma_f32 v20, v20, v162, -v158
	v_fma_f32 v21, v21, v162, -v158
	v_fma_f32 v22, v22, v162, -v158
	v_fma_f32 v23, v23, v162, -v158
	v_fma_f32 v16, v16, v162, -v158
	v_fma_f32 v17, v17, v162, -v158
	v_fma_f32 v18, v18, v162, -v158
	v_fma_f32 v19, v19, v162, -v158
	v_mul_f32_e32 v29, 0x3fb8aa3b, v29
	v_mul_f32_e32 v158, 0x3fb8aa3b, v26
	v_exp_f32_e32 v26, v28
	v_mul_f32_e32 v30, 0x3fb8aa3b, v30
	v_mul_f32_e32 v159, 0x3fb8aa3b, v27
	v_exp_f32_e32 v27, v29
	v_mul_f32_e32 v31, 0x3fb8aa3b, v31
	v_exp_f32_e32 v30, v30
	v_mul_f32_e32 v24, 0x3fb8aa3b, v24
	v_mul_f32_e32 v21, 0x3fb8aa3b, v21
	v_exp_f32_e32 v31, v31
	v_mul_f32_e32 v25, 0x3fb8aa3b, v25
	v_mul_f32_e32 v161, 0x3fb8aa3b, v19
	v_exp_f32_e32 v24, v24
	v_exp_f32_e32 v19, v21
	v_add_f32_e32 v21, 0, v26
	v_exp_f32_e32 v25, v25
	v_add_f32_e32 v21, v27, v21
	v_exp_f32_e32 v28, v158
	v_add_f32_e32 v21, v30, v21
	v_mul_f32_e32 v20, 0x3fb8aa3b, v20
	v_exp_f32_e32 v29, v159
	v_add_f32_e32 v21, v31, v21
	v_mul_f32_e32 v160, 0x3fb8aa3b, v18
	v_exp_f32_e32 v18, v20
	v_add_f32_e32 v21, v24, v21
	v_mul_f32_e32 v22, 0x3fb8aa3b, v22
	v_add_f32_e32 v21, v25, v21
	v_mul_f32_e32 v23, 0x3fb8aa3b, v23
	v_exp_f32_e32 v22, v22
	v_add_f32_e32 v21, v28, v21
	v_mul_f32_e32 v16, 0x3fb8aa3b, v16
	v_exp_f32_e32 v23, v23
	v_add_f32_e32 v21, v29, v21
	v_mul_f32_e32 v17, 0x3fb8aa3b, v17
	v_exp_f32_e32 v16, v16
	v_add_f32_e32 v21, v18, v21
	v_exp_f32_e32 v17, v17
	v_add_f32_e32 v21, v19, v21
	v_exp_f32_e32 v20, v160
	v_add_f32_e32 v21, v22, v21
	v_add_f32_e32 v158, v23, v21
	v_exp_f32_e32 v21, v161
	v_add_f32_e32 v158, v16, v158
	v_add_f32_e32 v158, v17, v158
	v_add_f32_e32 v158, v20, v158
	v_add_f32_e32 v158, v21, v158
	v_mov_b32_e32 v159, v158
	s_nop 1
	v_permlane16_swap_b32_e32 v158, v159
	s_waitcnt lgkmcnt(0)
	v_add_f32_e32 v158, v158, v159
	v_mov_b32_e32 v159, v158
	s_nop 1
	v_permlane32_swap_b32_e32 v158, v159
	s_and_saveexec_b64 s[24:25], s[4:5]
	s_cbranch_execz .LBB0_1028
	s_waitcnt lgkmcnt(0)
	v_add_f32_e32 v158, v158, v159
	ds_write_b32 v204, v158 offset:4096
.LBB0_1028:
	s_or_b64 exec, exec, s[24:25]
	s_waitcnt lgkmcnt(0)
	s_nop 0
	s_waitcnt lgkmcnt(0)
	s_nop 3
	s_nop 0
	s_nop 1
	ds_read_b128 v[158:161], v205
	s_waitcnt lgkmcnt(0)
	s_nop 1
	s_waitcnt lgkmcnt(0)
	v_max_f32_e32 v161, v161, v161
	v_max_f32_e32 v160, v160, v160
	v_max_f32_e32 v160, v160, v161
	v_max3_f32 v158, v158, v159, v160
	s_waitcnt lgkmcnt(0)
	s_nop 1
	v_mov_b32_e32 v162, v253
	s_nop 0
	v_fma_f32 v12, v12, v162, -v158
	v_fma_f32 v13, v13, v162, -v158
	v_fma_f32 v10, v10, v162, -v158
	v_mul_f32_e32 v12, 0x3fb8aa3b, v12
	v_fma_f32 v14, v14, v162, -v158
	v_fma_f32 v15, v15, v162, -v158
	v_fma_f32 v8, v8, v162, -v158
	v_fma_f32 v9, v9, v162, -v158
	v_fma_f32 v11, v11, v162, -v158
	v_fma_f32 v4, v4, v162, -v158
	v_fma_f32 v5, v5, v162, -v158
	v_fma_f32 v6, v6, v162, -v158
	v_fma_f32 v7, v7, v162, -v158
	v_fma_f32 v0, v0, v162, -v158
	v_fma_f32 v1, v1, v162, -v158
	v_fma_f32 v2, v2, v162, -v158
	v_fma_f32 v3, v3, v162, -v158
	v_mul_f32_e32 v13, 0x3fb8aa3b, v13
	v_mul_f32_e32 v158, 0x3fb8aa3b, v10
	v_exp_f32_e32 v10, v12
	v_mul_f32_e32 v14, 0x3fb8aa3b, v14
	v_mul_f32_e32 v159, 0x3fb8aa3b, v11
	v_exp_f32_e32 v11, v13
	v_mul_f32_e32 v15, 0x3fb8aa3b, v15
	v_exp_f32_e32 v14, v14
	v_mul_f32_e32 v8, 0x3fb8aa3b, v8
	v_mul_f32_e32 v5, 0x3fb8aa3b, v5
	v_exp_f32_e32 v15, v15
	v_mul_f32_e32 v9, 0x3fb8aa3b, v9
	v_mul_f32_e32 v161, 0x3fb8aa3b, v3
	v_exp_f32_e32 v8, v8
	v_exp_f32_e32 v3, v5
	v_add_f32_e32 v5, 0, v10
	v_exp_f32_e32 v9, v9
	v_add_f32_e32 v5, v11, v5
	v_exp_f32_e32 v12, v158
	v_add_f32_e32 v5, v14, v5
	v_mul_f32_e32 v4, 0x3fb8aa3b, v4
	v_exp_f32_e32 v13, v159
	v_add_f32_e32 v5, v15, v5
	v_mul_f32_e32 v160, 0x3fb8aa3b, v2
	v_exp_f32_e32 v2, v4
	v_add_f32_e32 v5, v8, v5
	v_mul_f32_e32 v6, 0x3fb8aa3b, v6
	v_add_f32_e32 v5, v9, v5
	v_mul_f32_e32 v7, 0x3fb8aa3b, v7
	v_exp_f32_e32 v6, v6
	v_add_f32_e32 v5, v12, v5
	v_mul_f32_e32 v0, 0x3fb8aa3b, v0
	v_exp_f32_e32 v7, v7
	v_add_f32_e32 v5, v13, v5
	v_mul_f32_e32 v1, 0x3fb8aa3b, v1
	v_exp_f32_e32 v0, v0
	v_add_f32_e32 v5, v2, v5
	v_exp_f32_e32 v1, v1
	v_add_f32_e32 v5, v3, v5
	v_exp_f32_e32 v4, v160
	v_add_f32_e32 v5, v6, v5
	v_add_f32_e32 v158, v7, v5
	v_exp_f32_e32 v5, v161
	v_add_f32_e32 v158, v0, v158
	v_add_f32_e32 v158, v1, v158
	v_add_f32_e32 v158, v4, v158
	v_add_f32_e32 v158, v5, v158
	v_mov_b32_e32 v159, v158
	s_nop 1
	v_permlane16_swap_b32_e32 v158, v159
	s_waitcnt lgkmcnt(0)
	v_add_f32_e32 v158, v158, v159
	v_mov_b32_e32 v159, v158
	s_nop 1
	v_permlane32_swap_b32_e32 v158, v159
	s_and_saveexec_b64 s[24:25], s[4:5]
	s_cbranch_execz .LBB0_1030
	s_waitcnt lgkmcnt(0)
	v_add_f32_e32 v158, v158, v159
	ds_write_b32 v206, v158 offset:4096
